# v7 + LDS-DMA group issued before the ds_reads in each load segment
# speedup vs baseline: 1.0077x; 1.0033x over previous
.LBB0_109:
	s_add_u32 s22, s20, 0xfff04000
	s_addc_u32 s23, s21, -1
	s_cmp_eq_u32 s46, 60
	s_cselect_b32 s26, s42, s22
	s_cselect_b32 s27, s15, s23
	s_cselect_b32 s24, s43, s44
	s_cselect_b32 s25, s13, s45
	s_add_u32 s22, s26, 0x4000
	s_addc_u32 s23, s27, 0
	s_add_i32 m0, s29, 0xc000
	s_nop 0
	global_load_lds_dwordx4 v146, s[20:21]
	s_add_i32 m0, s29, 0xe000
	s_nop 0
	global_load_lds_dwordx4 v148, s[20:21]
	ds_read_b128 v[130:133], v158
	ds_read_b128 v[162:165], v158 offset:1024
	ds_read_b128 v[166:169], v158 offset:2048
	ds_read_b128 v[170:173], v158 offset:3072
	ds_read_b128 v[174:177], v159
	ds_read_b128 v[178:181], v159 offset:1024
	ds_read_b128 v[182:185], v159 offset:2048
	ds_read_b128 v[186:189], v159 offset:3072
	ds_read_b128 v[190:193], v160
	ds_read_b128 v[194:197], v160 offset:1024
	ds_read_b128 v[198:201], v160 offset:2048
	ds_read_b128 v[202:205], v160 offset:3072
	ds_read_b128 v[206:209], v160 offset:4096
	ds_read_b128 v[210:213], v160 offset:5120
	ds_read_b128 v[214:217], v160 offset:6144
	ds_read_b128 v[218:221], v160 offset:7168
	s_waitcnt vmcnt(8)
	s_waitcnt lgkmcnt(0)
	s_barrier
	s_waitcnt lgkmcnt(0)
	v_mfma_f32_16x16x32_bf16 v[62:65], v[130:133], v[190:193], v[62:65]
	v_mfma_f32_16x16x32_bf16 v[62:65], v[162:165], v[194:197], v[62:65]
	v_mfma_f32_16x16x32_bf16 v[58:61], v[166:169], v[190:193], v[58:61]
	v_mfma_f32_16x16x32_bf16 v[58:61], v[170:173], v[194:197], v[58:61]
	v_mfma_f32_16x16x32_bf16 v[54:57], v[130:133], v[198:201], v[54:57]
	v_mfma_f32_16x16x32_bf16 v[54:57], v[162:165], v[202:205], v[54:57]
	v_mfma_f32_16x16x32_bf16 v[50:53], v[166:169], v[198:201], v[50:53]
	v_mfma_f32_16x16x32_bf16 v[50:53], v[170:173], v[202:205], v[50:53]
	v_mfma_f32_16x16x32_bf16 v[46:49], v[130:133], v[206:209], v[46:49]
	v_mfma_f32_16x16x32_bf16 v[46:49], v[162:165], v[210:213], v[46:49]
	v_mfma_f32_16x16x32_bf16 v[42:45], v[166:169], v[206:209], v[42:45]
	v_mfma_f32_16x16x32_bf16 v[42:45], v[170:173], v[210:213], v[42:45]
	v_mfma_f32_16x16x32_bf16 v[38:41], v[130:133], v[214:217], v[38:41]
	v_mfma_f32_16x16x32_bf16 v[38:41], v[162:165], v[218:221], v[38:41]
	v_mfma_f32_16x16x32_bf16 v[34:37], v[166:169], v[214:217], v[34:37]
	v_mfma_f32_16x16x32_bf16 v[34:37], v[170:173], v[218:221], v[34:37]
	v_mfma_f32_16x16x32_bf16 v[126:129], v[174:177], v[190:193], v[126:129]
	v_mfma_f32_16x16x32_bf16 v[126:129], v[178:181], v[194:197], v[126:129]
	v_mfma_f32_16x16x32_bf16 v[122:125], v[182:185], v[190:193], v[122:125]
	v_mfma_f32_16x16x32_bf16 v[122:125], v[186:189], v[194:197], v[122:125]
	v_mfma_f32_16x16x32_bf16 v[118:121], v[174:177], v[198:201], v[118:121]
	v_mfma_f32_16x16x32_bf16 v[118:121], v[178:181], v[202:205], v[118:121]
	v_mfma_f32_16x16x32_bf16 v[114:117], v[182:185], v[198:201], v[114:117]
	v_mfma_f32_16x16x32_bf16 v[114:117], v[186:189], v[202:205], v[114:117]
	v_mfma_f32_16x16x32_bf16 v[110:113], v[174:177], v[206:209], v[110:113]
	v_mfma_f32_16x16x32_bf16 v[110:113], v[178:181], v[210:213], v[110:113]
	v_mfma_f32_16x16x32_bf16 v[106:109], v[182:185], v[206:209], v[106:109]
	v_mfma_f32_16x16x32_bf16 v[106:109], v[186:189], v[210:213], v[106:109]
	v_mfma_f32_16x16x32_bf16 v[102:105], v[174:177], v[214:217], v[102:105]
	v_mfma_f32_16x16x32_bf16 v[102:105], v[178:181], v[218:221], v[102:105]
	v_mfma_f32_16x16x32_bf16 v[98:101], v[182:185], v[214:217], v[98:101]
	v_mfma_f32_16x16x32_bf16 v[98:101], v[186:189], v[218:221], v[98:101]
	s_barrier
	s_add_i32 s47, s36, s28
	s_mov_b32 m0, s47
	s_nop 0
	global_load_lds_dwordx4 v138, s[24:25]
	s_add_i32 m0, s47, 0x2000
	s_add_u32 s48, s24, 0x100000
	s_addc_u32 s49, s25, 0
	s_add_i32 s47, s37, s28
	global_load_lds_dwordx4 v134, s[24:25]
	s_mov_b32 m0, s47
	s_nop 0
	global_load_lds_dwordx4 v138, s[48:49]
	s_add_i32 m0, s47, 0x2000
	s_nop 0
	global_load_lds_dwordx4 v134, s[48:49]
	s_mov_b32 m0, s29
	s_nop 0
	global_load_lds_dwordx4 v140, s[26:27]
	s_mov_b32 m0, s30
	s_nop 0
	global_load_lds_dwordx4 v136, s[26:27]
	ds_read_b128 v[190:193], v160 offset:16384
	ds_read_b128 v[194:197], v160 offset:17408
	ds_read_b128 v[198:201], v160 offset:18432
	ds_read_b128 v[202:205], v160 offset:19456
	ds_read_b128 v[206:209], v160 offset:20480
	ds_read_b128 v[210:213], v160 offset:21504
	ds_read_b128 v[214:217], v160 offset:22528
	ds_read_b128 v[218:221], v160 offset:23552
	s_waitcnt vmcnt(8)
	s_waitcnt lgkmcnt(0)
	s_barrier
	s_waitcnt lgkmcnt(0)
	v_mfma_f32_16x16x32_bf16 v[30:33], v[130:133], v[190:193], v[30:33]
	v_mfma_f32_16x16x32_bf16 v[30:33], v[162:165], v[194:197], v[30:33]
	v_mfma_f32_16x16x32_bf16 v[26:29], v[166:169], v[190:193], v[26:29]
	v_mfma_f32_16x16x32_bf16 v[26:29], v[170:173], v[194:197], v[26:29]
	v_mfma_f32_16x16x32_bf16 v[22:25], v[130:133], v[198:201], v[22:25]
	v_mfma_f32_16x16x32_bf16 v[22:25], v[162:165], v[202:205], v[22:25]
	v_mfma_f32_16x16x32_bf16 v[18:21], v[166:169], v[198:201], v[18:21]
	v_mfma_f32_16x16x32_bf16 v[18:21], v[170:173], v[202:205], v[18:21]
	v_mfma_f32_16x16x32_bf16 v[14:17], v[130:133], v[206:209], v[14:17]
	v_mfma_f32_16x16x32_bf16 v[14:17], v[162:165], v[210:213], v[14:17]
	v_mfma_f32_16x16x32_bf16 v[10:13], v[166:169], v[206:209], v[10:13]
	v_mfma_f32_16x16x32_bf16 v[10:13], v[170:173], v[210:213], v[10:13]
	v_mfma_f32_16x16x32_bf16 v[6:9], v[130:133], v[214:217], v[6:9]
	v_mfma_f32_16x16x32_bf16 v[6:9], v[162:165], v[218:221], v[6:9]
	v_mfma_f32_16x16x32_bf16 v[2:5], v[166:169], v[214:217], v[2:5]
	v_mfma_f32_16x16x32_bf16 v[2:5], v[170:173], v[218:221], v[2:5]
	v_mfma_f32_16x16x32_bf16 v[94:97], v[174:177], v[190:193], v[94:97]
	v_mfma_f32_16x16x32_bf16 v[94:97], v[178:181], v[194:197], v[94:97]
	v_mfma_f32_16x16x32_bf16 v[90:93], v[182:185], v[190:193], v[90:93]
	v_mfma_f32_16x16x32_bf16 v[90:93], v[186:189], v[194:197], v[90:93]
	v_mfma_f32_16x16x32_bf16 v[86:89], v[174:177], v[198:201], v[86:89]
	v_mfma_f32_16x16x32_bf16 v[86:89], v[178:181], v[202:205], v[86:89]
	v_mfma_f32_16x16x32_bf16 v[82:85], v[182:185], v[198:201], v[82:85]
	v_mfma_f32_16x16x32_bf16 v[82:85], v[186:189], v[202:205], v[82:85]
	v_mfma_f32_16x16x32_bf16 v[78:81], v[174:177], v[206:209], v[78:81]
	v_mfma_f32_16x16x32_bf16 v[78:81], v[178:181], v[210:213], v[78:81]
	v_mfma_f32_16x16x32_bf16 v[74:77], v[182:185], v[206:209], v[74:77]
	v_mfma_f32_16x16x32_bf16 v[74:77], v[186:189], v[210:213], v[74:77]
	v_mfma_f32_16x16x32_bf16 v[70:73], v[174:177], v[214:217], v[70:73]
	v_mfma_f32_16x16x32_bf16 v[70:73], v[178:181], v[218:221], v[70:73]
	v_mfma_f32_16x16x32_bf16 v[66:69], v[182:185], v[214:217], v[66:69]
	v_mfma_f32_16x16x32_bf16 v[66:69], v[186:189], v[218:221], v[66:69]
	s_barrier
	s_add_i32 s47, 0, 0x18000
	s_add_i32 s48, 0, 0x1c000
	s_add_u32 s26, s26, 0x100000
	s_addc_u32 s27, s27, 0
	s_mov_b32 m0, s31
	s_nop 0
	global_load_lds_dwordx4 v140, s[26:27]
	s_mov_b32 m0, s33
	s_nop 0
	global_load_lds_dwordx4 v136, s[26:27]
	v_add_u32_e32 v154, s47, v156
	ds_read_b128 v[130:133], v154
	ds_read_b128 v[162:165], v154 offset:1024
	ds_read_b128 v[166:169], v154 offset:2048
	ds_read_b128 v[170:173], v154 offset:3072
	v_add_u32_e32 v154, s48, v156
	ds_read_b128 v[174:177], v154
	ds_read_b128 v[178:181], v154 offset:1024
	ds_read_b128 v[182:185], v154 offset:2048
	ds_read_b128 v[186:189], v154 offset:3072
	ds_read_b128 v[190:193], v160 offset:32768
	ds_read_b128 v[194:197], v160 offset:33792
	ds_read_b128 v[198:201], v160 offset:34816
	ds_read_b128 v[202:205], v160 offset:35840
	ds_read_b128 v[206:209], v160 offset:36864
	ds_read_b128 v[210:213], v160 offset:37888
	ds_read_b128 v[214:217], v160 offset:38912
	ds_read_b128 v[218:221], v160 offset:39936
	s_waitcnt vmcnt(8)
	s_waitcnt lgkmcnt(0)
	s_barrier
	s_waitcnt lgkmcnt(0)
	v_mfma_f32_16x16x32_bf16 v[62:65], v[130:133], v[190:193], v[62:65]
	v_mfma_f32_16x16x32_bf16 v[62:65], v[162:165], v[194:197], v[62:65]
	v_mfma_f32_16x16x32_bf16 v[58:61], v[166:169], v[190:193], v[58:61]
	v_mfma_f32_16x16x32_bf16 v[58:61], v[170:173], v[194:197], v[58:61]
	v_mfma_f32_16x16x32_bf16 v[54:57], v[130:133], v[198:201], v[54:57]
	v_mfma_f32_16x16x32_bf16 v[54:57], v[162:165], v[202:205], v[54:57]
	v_mfma_f32_16x16x32_bf16 v[50:53], v[166:169], v[198:201], v[50:53]
	v_mfma_f32_16x16x32_bf16 v[50:53], v[170:173], v[202:205], v[50:53]
	v_mfma_f32_16x16x32_bf16 v[46:49], v[130:133], v[206:209], v[46:49]
	v_mfma_f32_16x16x32_bf16 v[46:49], v[162:165], v[210:213], v[46:49]
	v_mfma_f32_16x16x32_bf16 v[42:45], v[166:169], v[206:209], v[42:45]
	v_mfma_f32_16x16x32_bf16 v[42:45], v[170:173], v[210:213], v[42:45]
	v_mfma_f32_16x16x32_bf16 v[38:41], v[130:133], v[214:217], v[38:41]
	v_mfma_f32_16x16x32_bf16 v[38:41], v[162:165], v[218:221], v[38:41]
	v_mfma_f32_16x16x32_bf16 v[34:37], v[166:169], v[214:217], v[34:37]
	v_mfma_f32_16x16x32_bf16 v[34:37], v[170:173], v[218:221], v[34:37]
	v_mfma_f32_16x16x32_bf16 v[126:129], v[174:177], v[190:193], v[126:129]
	v_mfma_f32_16x16x32_bf16 v[126:129], v[178:181], v[194:197], v[126:129]
	v_mfma_f32_16x16x32_bf16 v[122:125], v[182:185], v[190:193], v[122:125]
	v_mfma_f32_16x16x32_bf16 v[122:125], v[186:189], v[194:197], v[122:125]
	v_mfma_f32_16x16x32_bf16 v[118:121], v[174:177], v[198:201], v[118:121]
	v_mfma_f32_16x16x32_bf16 v[118:121], v[178:181], v[202:205], v[118:121]
	v_mfma_f32_16x16x32_bf16 v[114:117], v[182:185], v[198:201], v[114:117]
	v_mfma_f32_16x16x32_bf16 v[114:117], v[186:189], v[202:205], v[114:117]
	v_mfma_f32_16x16x32_bf16 v[110:113], v[174:177], v[206:209], v[110:113]
	v_mfma_f32_16x16x32_bf16 v[110:113], v[178:181], v[210:213], v[110:113]
	v_mfma_f32_16x16x32_bf16 v[106:109], v[182:185], v[206:209], v[106:109]
	v_mfma_f32_16x16x32_bf16 v[106:109], v[186:189], v[210:213], v[106:109]
	v_mfma_f32_16x16x32_bf16 v[102:105], v[174:177], v[214:217], v[102:105]
	v_mfma_f32_16x16x32_bf16 v[102:105], v[178:181], v[218:221], v[102:105]
	v_mfma_f32_16x16x32_bf16 v[98:101], v[182:185], v[214:217], v[98:101]
	v_mfma_f32_16x16x32_bf16 v[98:101], v[186:189], v[218:221], v[98:101]
	s_barrier
	s_add_u32 s26, s24, 0x4000
	s_addc_u32 s27, s25, 0
	s_add_i32 s47, s47, s28
	s_mov_b32 m0, s47
	s_nop 0
	global_load_lds_dwordx4 v138, s[26:27]
	s_add_i32 m0, s47, 0x2000
	s_add_u32 s24, s24, 0x104000
	s_addc_u32 s25, s25, 0
	global_load_lds_dwordx4 v134, s[26:27]
	s_add_i32 s26, s48, s28
	s_mov_b32 m0, s26
	s_nop 0
	global_load_lds_dwordx4 v138, s[24:25]
	s_add_i32 m0, s26, 0x2000
	s_nop 0
	global_load_lds_dwordx4 v134, s[24:25]
	s_mov_b32 m0, s34
	s_nop 0
	global_load_lds_dwordx4 v140, s[22:23]
	s_mov_b32 m0, s35
	s_nop 0
	global_load_lds_dwordx4 v136, s[22:23]
	ds_read_b128 v[190:193], v160 offset:49152
	ds_read_b128 v[194:197], v160 offset:50176
	ds_read_b128 v[198:201], v160 offset:51200
	ds_read_b128 v[202:205], v160 offset:52224
	ds_read_b128 v[206:209], v160 offset:53248
	ds_read_b128 v[210:213], v160 offset:54272
	ds_read_b128 v[214:217], v160 offset:55296
	ds_read_b128 v[218:221], v160 offset:56320
	s_waitcnt vmcnt(8)
	s_waitcnt lgkmcnt(0)
	s_barrier
	s_waitcnt lgkmcnt(0)
	v_mfma_f32_16x16x32_bf16 v[30:33], v[130:133], v[190:193], v[30:33]
	v_mfma_f32_16x16x32_bf16 v[30:33], v[162:165], v[194:197], v[30:33]
	v_mfma_f32_16x16x32_bf16 v[26:29], v[166:169], v[190:193], v[26:29]
	v_mfma_f32_16x16x32_bf16 v[26:29], v[170:173], v[194:197], v[26:29]
	v_mfma_f32_16x16x32_bf16 v[22:25], v[130:133], v[198:201], v[22:25]
	v_mfma_f32_16x16x32_bf16 v[22:25], v[162:165], v[202:205], v[22:25]
	v_mfma_f32_16x16x32_bf16 v[18:21], v[166:169], v[198:201], v[18:21]
	v_mfma_f32_16x16x32_bf16 v[18:21], v[170:173], v[202:205], v[18:21]
	v_mfma_f32_16x16x32_bf16 v[14:17], v[130:133], v[206:209], v[14:17]
	v_mfma_f32_16x16x32_bf16 v[14:17], v[162:165], v[210:213], v[14:17]
	v_mfma_f32_16x16x32_bf16 v[10:13], v[166:169], v[206:209], v[10:13]
	v_mfma_f32_16x16x32_bf16 v[10:13], v[170:173], v[210:213], v[10:13]
	v_mfma_f32_16x16x32_bf16 v[6:9], v[130:133], v[214:217], v[6:9]
	v_mfma_f32_16x16x32_bf16 v[6:9], v[162:165], v[218:221], v[6:9]
	v_mfma_f32_16x16x32_bf16 v[2:5], v[166:169], v[214:217], v[2:5]
	v_mfma_f32_16x16x32_bf16 v[2:5], v[170:173], v[218:221], v[2:5]
	v_mfma_f32_16x16x32_bf16 v[94:97], v[174:177], v[190:193], v[94:97]
	v_mfma_f32_16x16x32_bf16 v[94:97], v[178:181], v[194:197], v[94:97]
	v_mfma_f32_16x16x32_bf16 v[90:93], v[182:185], v[190:193], v[90:93]
	v_mfma_f32_16x16x32_bf16 v[90:93], v[186:189], v[194:197], v[90:93]
	v_mfma_f32_16x16x32_bf16 v[86:89], v[174:177], v[198:201], v[86:89]
	v_mfma_f32_16x16x32_bf16 v[86:89], v[178:181], v[202:205], v[86:89]
	v_mfma_f32_16x16x32_bf16 v[82:85], v[182:185], v[198:201], v[82:85]
	v_mfma_f32_16x16x32_bf16 v[82:85], v[186:189], v[202:205], v[82:85]
	v_mfma_f32_16x16x32_bf16 v[78:81], v[174:177], v[206:209], v[78:81]
	v_mfma_f32_16x16x32_bf16 v[78:81], v[178:181], v[210:213], v[78:81]
	v_mfma_f32_16x16x32_bf16 v[74:77], v[182:185], v[206:209], v[74:77]
	v_mfma_f32_16x16x32_bf16 v[74:77], v[186:189], v[210:213], v[74:77]
	v_mfma_f32_16x16x32_bf16 v[70:73], v[174:177], v[214:217], v[70:73]
	v_mfma_f32_16x16x32_bf16 v[70:73], v[178:181], v[218:221], v[70:73]
	v_mfma_f32_16x16x32_bf16 v[66:69], v[182:185], v[214:217], v[66:69]
	v_mfma_f32_16x16x32_bf16 v[66:69], v[186:189], v[218:221], v[66:69]
	s_barrier
	s_add_i32 s46, s46, 2
	s_add_u32 s20, s20, 0x8000
	s_addc_u32 s21, s21, 0
	s_add_u32 s44, s44, 0x8000
	s_addc_u32 s45, s45, 0
	s_cmp_gt_u32 s46, 61
	s_cbranch_scc0 .LBB0_109
	s_and_b64 vcc, exec, s[8:9]
	s_cbranch_vccnz .LBB0_113
	v_lshl_add_u32 v154, s4, 8, v1
	s_cmp_lg_u32 s41, 24
	s_mov_b64 s[20:21], -1
	s_cbranch_scc1 .LBB0_114

.LBB0_376:
	s_add_u32 s34, s26, 0xfff04000
	s_addc_u32 s35, s27, -1
	s_cmp_eq_u32 s87, 60
	s_cselect_b32 s38, s80, s34
	s_cselect_b32 s39, s21, s35
	s_cselect_b32 s36, s81, s83
	s_cselect_b32 s37, s19, s86
	s_add_u32 s34, s38, 0x4000
	s_addc_u32 s35, s39, 0
	s_add_i32 m0, s46, 0xc000
	s_nop 0
	global_load_lds_dwordx4 v146, s[26:27]
	s_add_i32 m0, s46, 0xe000
	s_nop 0
	global_load_lds_dwordx4 v148, s[26:27]
	ds_read_b128 v[130:133], v159
	ds_read_b128 v[162:165], v159 offset:1024
	ds_read_b128 v[166:169], v159 offset:2048
	ds_read_b128 v[170:173], v159 offset:3072
	ds_read_b128 v[174:177], v160
	ds_read_b128 v[178:181], v160 offset:1024
	ds_read_b128 v[182:185], v160 offset:2048
	ds_read_b128 v[186:189], v160 offset:3072
	ds_read_b128 v[190:193], v161
	ds_read_b128 v[194:197], v161 offset:1024
	ds_read_b128 v[198:201], v161 offset:2048
	ds_read_b128 v[202:205], v161 offset:3072
	ds_read_b128 v[206:209], v161 offset:4096
	ds_read_b128 v[210:213], v161 offset:5120
	ds_read_b128 v[214:217], v161 offset:6144
	ds_read_b128 v[218:221], v161 offset:7168
	s_waitcnt vmcnt(8)
	s_waitcnt lgkmcnt(0)
	s_barrier
	s_waitcnt lgkmcnt(0)
	v_mfma_f32_16x16x32_bf16 v[62:65], v[130:133], v[190:193], v[62:65]
	v_mfma_f32_16x16x32_bf16 v[62:65], v[162:165], v[194:197], v[62:65]
	v_mfma_f32_16x16x32_bf16 v[58:61], v[166:169], v[190:193], v[58:61]
	v_mfma_f32_16x16x32_bf16 v[58:61], v[170:173], v[194:197], v[58:61]
	v_mfma_f32_16x16x32_bf16 v[54:57], v[130:133], v[198:201], v[54:57]
	v_mfma_f32_16x16x32_bf16 v[54:57], v[162:165], v[202:205], v[54:57]
	v_mfma_f32_16x16x32_bf16 v[50:53], v[166:169], v[198:201], v[50:53]
	v_mfma_f32_16x16x32_bf16 v[50:53], v[170:173], v[202:205], v[50:53]
	v_mfma_f32_16x16x32_bf16 v[46:49], v[130:133], v[206:209], v[46:49]
	v_mfma_f32_16x16x32_bf16 v[46:49], v[162:165], v[210:213], v[46:49]
	v_mfma_f32_16x16x32_bf16 v[42:45], v[166:169], v[206:209], v[42:45]
	v_mfma_f32_16x16x32_bf16 v[42:45], v[170:173], v[210:213], v[42:45]
	v_mfma_f32_16x16x32_bf16 v[38:41], v[130:133], v[214:217], v[38:41]
	v_mfma_f32_16x16x32_bf16 v[38:41], v[162:165], v[218:221], v[38:41]
	v_mfma_f32_16x16x32_bf16 v[34:37], v[166:169], v[214:217], v[34:37]
	v_mfma_f32_16x16x32_bf16 v[34:37], v[170:173], v[218:221], v[34:37]
	v_mfma_f32_16x16x32_bf16 v[126:129], v[174:177], v[190:193], v[126:129]
	v_mfma_f32_16x16x32_bf16 v[126:129], v[178:181], v[194:197], v[126:129]
	v_mfma_f32_16x16x32_bf16 v[122:125], v[182:185], v[190:193], v[122:125]
	v_mfma_f32_16x16x32_bf16 v[122:125], v[186:189], v[194:197], v[122:125]
	v_mfma_f32_16x16x32_bf16 v[118:121], v[174:177], v[198:201], v[118:121]
	v_mfma_f32_16x16x32_bf16 v[118:121], v[178:181], v[202:205], v[118:121]
	v_mfma_f32_16x16x32_bf16 v[114:117], v[182:185], v[198:201], v[114:117]
	v_mfma_f32_16x16x32_bf16 v[114:117], v[186:189], v[202:205], v[114:117]
	v_mfma_f32_16x16x32_bf16 v[110:113], v[174:177], v[206:209], v[110:113]
	v_mfma_f32_16x16x32_bf16 v[110:113], v[178:181], v[210:213], v[110:113]
	v_mfma_f32_16x16x32_bf16 v[106:109], v[182:185], v[206:209], v[106:109]
	v_mfma_f32_16x16x32_bf16 v[106:109], v[186:189], v[210:213], v[106:109]
	v_mfma_f32_16x16x32_bf16 v[102:105], v[174:177], v[214:217], v[102:105]
	v_mfma_f32_16x16x32_bf16 v[102:105], v[178:181], v[218:221], v[102:105]
	v_mfma_f32_16x16x32_bf16 v[98:101], v[182:185], v[214:217], v[98:101]
	v_mfma_f32_16x16x32_bf16 v[98:101], v[186:189], v[218:221], v[98:101]
	s_barrier
	s_add_i32 s88, s66, s41
	s_mov_b32 m0, s88
	s_nop 0
	global_load_lds_dwordx4 v138, s[36:37]
	s_add_i32 m0, s88, 0x2000
	s_add_u32 s88, s36, 0x100000
	s_addc_u32 s89, s37, 0
	s_add_i32 vcc_lo, s67, s41
	global_load_lds_dwordx4 v134, s[36:37]
	s_mov_b32 m0, vcc_lo
	s_nop 0
	global_load_lds_dwordx4 v138, s[88:89]
	s_add_i32 m0, vcc_lo, 0x2000
	s_nop 0
	global_load_lds_dwordx4 v134, s[88:89]
	s_mov_b32 m0, s46
	s_nop 0
	global_load_lds_dwordx4 v140, s[38:39]
	s_mov_b32 m0, s47
	s_nop 0
	global_load_lds_dwordx4 v136, s[38:39]
	ds_read_b128 v[190:193], v161 offset:16384
	ds_read_b128 v[194:197], v161 offset:17408
	ds_read_b128 v[198:201], v161 offset:18432
	ds_read_b128 v[202:205], v161 offset:19456
	ds_read_b128 v[206:209], v161 offset:20480
	ds_read_b128 v[210:213], v161 offset:21504
	ds_read_b128 v[214:217], v161 offset:22528
	ds_read_b128 v[218:221], v161 offset:23552
	s_waitcnt vmcnt(8)
	s_waitcnt lgkmcnt(0)
	s_barrier
	s_waitcnt lgkmcnt(0)
	v_mfma_f32_16x16x32_bf16 v[30:33], v[130:133], v[190:193], v[30:33]
	v_mfma_f32_16x16x32_bf16 v[30:33], v[162:165], v[194:197], v[30:33]
	v_mfma_f32_16x16x32_bf16 v[26:29], v[166:169], v[190:193], v[26:29]
	v_mfma_f32_16x16x32_bf16 v[26:29], v[170:173], v[194:197], v[26:29]
	v_mfma_f32_16x16x32_bf16 v[22:25], v[130:133], v[198:201], v[22:25]
	v_mfma_f32_16x16x32_bf16 v[22:25], v[162:165], v[202:205], v[22:25]
	v_mfma_f32_16x16x32_bf16 v[18:21], v[166:169], v[198:201], v[18:21]
	v_mfma_f32_16x16x32_bf16 v[18:21], v[170:173], v[202:205], v[18:21]
	v_mfma_f32_16x16x32_bf16 v[14:17], v[130:133], v[206:209], v[14:17]
	v_mfma_f32_16x16x32_bf16 v[14:17], v[162:165], v[210:213], v[14:17]
	v_mfma_f32_16x16x32_bf16 v[10:13], v[166:169], v[206:209], v[10:13]
	v_mfma_f32_16x16x32_bf16 v[10:13], v[170:173], v[210:213], v[10:13]
	v_mfma_f32_16x16x32_bf16 v[6:9], v[130:133], v[214:217], v[6:9]
	v_mfma_f32_16x16x32_bf16 v[6:9], v[162:165], v[218:221], v[6:9]
	v_mfma_f32_16x16x32_bf16 v[2:5], v[166:169], v[214:217], v[2:5]
	v_mfma_f32_16x16x32_bf16 v[2:5], v[170:173], v[218:221], v[2:5]
	v_mfma_f32_16x16x32_bf16 v[94:97], v[174:177], v[190:193], v[94:97]
	v_mfma_f32_16x16x32_bf16 v[94:97], v[178:181], v[194:197], v[94:97]
	v_mfma_f32_16x16x32_bf16 v[90:93], v[182:185], v[190:193], v[90:93]
	v_mfma_f32_16x16x32_bf16 v[90:93], v[186:189], v[194:197], v[90:93]
	v_mfma_f32_16x16x32_bf16 v[86:89], v[174:177], v[198:201], v[86:89]
	v_mfma_f32_16x16x32_bf16 v[86:89], v[178:181], v[202:205], v[86:89]
	v_mfma_f32_16x16x32_bf16 v[82:85], v[182:185], v[198:201], v[82:85]
	v_mfma_f32_16x16x32_bf16 v[82:85], v[186:189], v[202:205], v[82:85]
	v_mfma_f32_16x16x32_bf16 v[78:81], v[174:177], v[206:209], v[78:81]
	v_mfma_f32_16x16x32_bf16 v[78:81], v[178:181], v[210:213], v[78:81]
	v_mfma_f32_16x16x32_bf16 v[74:77], v[182:185], v[206:209], v[74:77]
	v_mfma_f32_16x16x32_bf16 v[74:77], v[186:189], v[210:213], v[74:77]
	v_mfma_f32_16x16x32_bf16 v[70:73], v[174:177], v[214:217], v[70:73]
	v_mfma_f32_16x16x32_bf16 v[70:73], v[178:181], v[218:221], v[70:73]
	v_mfma_f32_16x16x32_bf16 v[66:69], v[182:185], v[214:217], v[66:69]
	v_mfma_f32_16x16x32_bf16 v[66:69], v[186:189], v[218:221], v[66:69]
	s_barrier
	s_add_i32 s88, 0, 0x18000
	s_add_i32 s89, 0, 0x1c000
	s_add_u32 s38, s38, 0x100000
	s_addc_u32 s39, s39, 0
	s_mov_b32 m0, s58
	s_nop 0
	global_load_lds_dwordx4 v140, s[38:39]
	s_mov_b32 m0, s59
	s_nop 0
	global_load_lds_dwordx4 v136, s[38:39]
	v_add_u32_e32 v154, s88, v157
	ds_read_b128 v[130:133], v154
	ds_read_b128 v[162:165], v154 offset:1024
	ds_read_b128 v[166:169], v154 offset:2048
	ds_read_b128 v[170:173], v154 offset:3072
	v_add_u32_e32 v154, s89, v157
	ds_read_b128 v[174:177], v154
	ds_read_b128 v[178:181], v154 offset:1024
	ds_read_b128 v[182:185], v154 offset:2048
	ds_read_b128 v[186:189], v154 offset:3072
	ds_read_b128 v[190:193], v161 offset:32768
	ds_read_b128 v[194:197], v161 offset:33792
	ds_read_b128 v[198:201], v161 offset:34816
	ds_read_b128 v[202:205], v161 offset:35840
	ds_read_b128 v[206:209], v161 offset:36864
	ds_read_b128 v[210:213], v161 offset:37888
	ds_read_b128 v[214:217], v161 offset:38912
	ds_read_b128 v[218:221], v161 offset:39936
	s_waitcnt vmcnt(8)
	s_waitcnt lgkmcnt(0)
	s_barrier
	s_waitcnt lgkmcnt(0)
	v_mfma_f32_16x16x32_bf16 v[62:65], v[130:133], v[190:193], v[62:65]
	v_mfma_f32_16x16x32_bf16 v[62:65], v[162:165], v[194:197], v[62:65]
	v_mfma_f32_16x16x32_bf16 v[58:61], v[166:169], v[190:193], v[58:61]
	v_mfma_f32_16x16x32_bf16 v[58:61], v[170:173], v[194:197], v[58:61]
	v_mfma_f32_16x16x32_bf16 v[54:57], v[130:133], v[198:201], v[54:57]
	v_mfma_f32_16x16x32_bf16 v[54:57], v[162:165], v[202:205], v[54:57]
	v_mfma_f32_16x16x32_bf16 v[50:53], v[166:169], v[198:201], v[50:53]
	v_mfma_f32_16x16x32_bf16 v[50:53], v[170:173], v[202:205], v[50:53]
	v_mfma_f32_16x16x32_bf16 v[46:49], v[130:133], v[206:209], v[46:49]
	v_mfma_f32_16x16x32_bf16 v[46:49], v[162:165], v[210:213], v[46:49]
	v_mfma_f32_16x16x32_bf16 v[42:45], v[166:169], v[206:209], v[42:45]
	v_mfma_f32_16x16x32_bf16 v[42:45], v[170:173], v[210:213], v[42:45]
	v_mfma_f32_16x16x32_bf16 v[38:41], v[130:133], v[214:217], v[38:41]
	v_mfma_f32_16x16x32_bf16 v[38:41], v[162:165], v[218:221], v[38:41]
	v_mfma_f32_16x16x32_bf16 v[34:37], v[166:169], v[214:217], v[34:37]
	v_mfma_f32_16x16x32_bf16 v[34:37], v[170:173], v[218:221], v[34:37]
	v_mfma_f32_16x16x32_bf16 v[126:129], v[174:177], v[190:193], v[126:129]
	v_mfma_f32_16x16x32_bf16 v[126:129], v[178:181], v[194:197], v[126:129]
	v_mfma_f32_16x16x32_bf16 v[122:125], v[182:185], v[190:193], v[122:125]
	v_mfma_f32_16x16x32_bf16 v[122:125], v[186:189], v[194:197], v[122:125]
	v_mfma_f32_16x16x32_bf16 v[118:121], v[174:177], v[198:201], v[118:121]
	v_mfma_f32_16x16x32_bf16 v[118:121], v[178:181], v[202:205], v[118:121]
	v_mfma_f32_16x16x32_bf16 v[114:117], v[182:185], v[198:201], v[114:117]
	v_mfma_f32_16x16x32_bf16 v[114:117], v[186:189], v[202:205], v[114:117]
	v_mfma_f32_16x16x32_bf16 v[110:113], v[174:177], v[206:209], v[110:113]
	v_mfma_f32_16x16x32_bf16 v[110:113], v[178:181], v[210:213], v[110:113]
	v_mfma_f32_16x16x32_bf16 v[106:109], v[182:185], v[206:209], v[106:109]
	v_mfma_f32_16x16x32_bf16 v[106:109], v[186:189], v[210:213], v[106:109]
	v_mfma_f32_16x16x32_bf16 v[102:105], v[174:177], v[214:217], v[102:105]
	v_mfma_f32_16x16x32_bf16 v[102:105], v[178:181], v[218:221], v[102:105]
	v_mfma_f32_16x16x32_bf16 v[98:101], v[182:185], v[214:217], v[98:101]
	v_mfma_f32_16x16x32_bf16 v[98:101], v[186:189], v[218:221], v[98:101]
	s_barrier
	s_add_u32 s38, s36, 0x4000
	s_addc_u32 s39, s37, 0
	s_add_i32 s88, s88, s41
	s_mov_b32 m0, s88
	s_nop 0
	global_load_lds_dwordx4 v138, s[38:39]
	s_add_i32 m0, s88, 0x2000
	s_add_u32 s36, s36, 0x104000
	s_addc_u32 s37, s37, 0
	global_load_lds_dwordx4 v134, s[38:39]
	s_add_i32 s38, s89, s41
	s_mov_b32 m0, s38
	s_nop 0
	global_load_lds_dwordx4 v138, s[36:37]
	s_add_i32 m0, s38, 0x2000
	s_nop 0
	global_load_lds_dwordx4 v134, s[36:37]
	s_mov_b32 m0, s64
	s_nop 0
	global_load_lds_dwordx4 v140, s[34:35]
	s_mov_b32 m0, s65
	s_nop 0
	global_load_lds_dwordx4 v136, s[34:35]
	ds_read_b128 v[190:193], v161 offset:49152
	ds_read_b128 v[194:197], v161 offset:50176
	ds_read_b128 v[198:201], v161 offset:51200
	ds_read_b128 v[202:205], v161 offset:52224
	ds_read_b128 v[206:209], v161 offset:53248
	ds_read_b128 v[210:213], v161 offset:54272
	ds_read_b128 v[214:217], v161 offset:55296
	ds_read_b128 v[218:221], v161 offset:56320
	s_waitcnt vmcnt(8)
	s_waitcnt lgkmcnt(0)
	s_barrier
	s_waitcnt lgkmcnt(0)
	v_mfma_f32_16x16x32_bf16 v[30:33], v[130:133], v[190:193], v[30:33]
	v_mfma_f32_16x16x32_bf16 v[30:33], v[162:165], v[194:197], v[30:33]
	v_mfma_f32_16x16x32_bf16 v[26:29], v[166:169], v[190:193], v[26:29]
	v_mfma_f32_16x16x32_bf16 v[26:29], v[170:173], v[194:197], v[26:29]
	v_mfma_f32_16x16x32_bf16 v[22:25], v[130:133], v[198:201], v[22:25]
	v_mfma_f32_16x16x32_bf16 v[22:25], v[162:165], v[202:205], v[22:25]
	v_mfma_f32_16x16x32_bf16 v[18:21], v[166:169], v[198:201], v[18:21]
	v_mfma_f32_16x16x32_bf16 v[18:21], v[170:173], v[202:205], v[18:21]
	v_mfma_f32_16x16x32_bf16 v[14:17], v[130:133], v[206:209], v[14:17]
	v_mfma_f32_16x16x32_bf16 v[14:17], v[162:165], v[210:213], v[14:17]
	v_mfma_f32_16x16x32_bf16 v[10:13], v[166:169], v[206:209], v[10:13]
	v_mfma_f32_16x16x32_bf16 v[10:13], v[170:173], v[210:213], v[10:13]
	v_mfma_f32_16x16x32_bf16 v[6:9], v[130:133], v[214:217], v[6:9]
	v_mfma_f32_16x16x32_bf16 v[6:9], v[162:165], v[218:221], v[6:9]
	v_mfma_f32_16x16x32_bf16 v[2:5], v[166:169], v[214:217], v[2:5]
	v_mfma_f32_16x16x32_bf16 v[2:5], v[170:173], v[218:221], v[2:5]
	v_mfma_f32_16x16x32_bf16 v[94:97], v[174:177], v[190:193], v[94:97]
	v_mfma_f32_16x16x32_bf16 v[94:97], v[178:181], v[194:197], v[94:97]
	v_mfma_f32_16x16x32_bf16 v[90:93], v[182:185], v[190:193], v[90:93]
	v_mfma_f32_16x16x32_bf16 v[90:93], v[186:189], v[194:197], v[90:93]
	v_mfma_f32_16x16x32_bf16 v[86:89], v[174:177], v[198:201], v[86:89]
	v_mfma_f32_16x16x32_bf16 v[86:89], v[178:181], v[202:205], v[86:89]
	v_mfma_f32_16x16x32_bf16 v[82:85], v[182:185], v[198:201], v[82:85]
	v_mfma_f32_16x16x32_bf16 v[82:85], v[186:189], v[202:205], v[82:85]
	v_mfma_f32_16x16x32_bf16 v[78:81], v[174:177], v[206:209], v[78:81]
	v_mfma_f32_16x16x32_bf16 v[78:81], v[178:181], v[210:213], v[78:81]
	v_mfma_f32_16x16x32_bf16 v[74:77], v[182:185], v[206:209], v[74:77]
	v_mfma_f32_16x16x32_bf16 v[74:77], v[186:189], v[210:213], v[74:77]
	v_mfma_f32_16x16x32_bf16 v[70:73], v[174:177], v[214:217], v[70:73]
	v_mfma_f32_16x16x32_bf16 v[70:73], v[178:181], v[218:221], v[70:73]
	v_mfma_f32_16x16x32_bf16 v[66:69], v[182:185], v[214:217], v[66:69]
	v_mfma_f32_16x16x32_bf16 v[66:69], v[186:189], v[218:221], v[66:69]
	s_barrier
	s_add_i32 s87, s87, 2
	s_add_u32 s26, s26, 0x8000
	s_addc_u32 s27, s27, 0
	s_add_u32 s83, s83, 0x8000
	s_addc_u32 s86, s86, 0
	s_cmp_gt_u32 s87, 61
	s_cbranch_scc0 .LBB0_376
	s_and_b64 vcc, exec, s[14:15]
	s_cbranch_vccz .LBB0_379
	s_barrier

.LBB0_536:
	s_add_u32 s30, s26, 0xfff04000
	s_addc_u32 s31, s27, -1
	s_cmp_eq_u32 s80, 60
	s_cselect_b32 s36, s74, s30
	s_cselect_b32 s37, s21, s31
	s_cselect_b32 s34, s75, s78
	s_cselect_b32 s35, s19, s79
	s_add_u32 s30, s36, 0x4000
	s_addc_u32 s31, s37, 0
	s_add_i32 m0, s42, 0xc000
	s_nop 0
	global_load_lds_dwordx4 v146, s[26:27]
	s_add_i32 m0, s42, 0xe000
	s_nop 0
	global_load_lds_dwordx4 v148, s[26:27]
	ds_read_b128 v[130:133], v159
	ds_read_b128 v[162:165], v159 offset:1024
	ds_read_b128 v[166:169], v159 offset:2048
	ds_read_b128 v[170:173], v159 offset:3072
	ds_read_b128 v[174:177], v160
	ds_read_b128 v[178:181], v160 offset:1024
	ds_read_b128 v[182:185], v160 offset:2048
	ds_read_b128 v[186:189], v160 offset:3072
	ds_read_b128 v[190:193], v161
	ds_read_b128 v[194:197], v161 offset:1024
	ds_read_b128 v[198:201], v161 offset:2048
	ds_read_b128 v[202:205], v161 offset:3072
	ds_read_b128 v[206:209], v161 offset:4096
	ds_read_b128 v[210:213], v161 offset:5120
	ds_read_b128 v[214:217], v161 offset:6144
	ds_read_b128 v[218:221], v161 offset:7168
	s_waitcnt vmcnt(8)
	s_waitcnt lgkmcnt(0)
	s_barrier
	s_waitcnt lgkmcnt(0)
	v_mfma_f32_16x16x32_bf16 v[62:65], v[130:133], v[190:193], v[62:65]
	v_mfma_f32_16x16x32_bf16 v[62:65], v[162:165], v[194:197], v[62:65]
	v_mfma_f32_16x16x32_bf16 v[58:61], v[166:169], v[190:193], v[58:61]
	v_mfma_f32_16x16x32_bf16 v[58:61], v[170:173], v[194:197], v[58:61]
	v_mfma_f32_16x16x32_bf16 v[54:57], v[130:133], v[198:201], v[54:57]
	v_mfma_f32_16x16x32_bf16 v[54:57], v[162:165], v[202:205], v[54:57]
	v_mfma_f32_16x16x32_bf16 v[50:53], v[166:169], v[198:201], v[50:53]
	v_mfma_f32_16x16x32_bf16 v[50:53], v[170:173], v[202:205], v[50:53]
	v_mfma_f32_16x16x32_bf16 v[46:49], v[130:133], v[206:209], v[46:49]
	v_mfma_f32_16x16x32_bf16 v[46:49], v[162:165], v[210:213], v[46:49]
	v_mfma_f32_16x16x32_bf16 v[42:45], v[166:169], v[206:209], v[42:45]
	v_mfma_f32_16x16x32_bf16 v[42:45], v[170:173], v[210:213], v[42:45]
	v_mfma_f32_16x16x32_bf16 v[38:41], v[130:133], v[214:217], v[38:41]
	v_mfma_f32_16x16x32_bf16 v[38:41], v[162:165], v[218:221], v[38:41]
	v_mfma_f32_16x16x32_bf16 v[34:37], v[166:169], v[214:217], v[34:37]
	v_mfma_f32_16x16x32_bf16 v[34:37], v[170:173], v[218:221], v[34:37]
	v_mfma_f32_16x16x32_bf16 v[126:129], v[174:177], v[190:193], v[126:129]
	v_mfma_f32_16x16x32_bf16 v[126:129], v[178:181], v[194:197], v[126:129]
	v_mfma_f32_16x16x32_bf16 v[122:125], v[182:185], v[190:193], v[122:125]
	v_mfma_f32_16x16x32_bf16 v[122:125], v[186:189], v[194:197], v[122:125]
	v_mfma_f32_16x16x32_bf16 v[118:121], v[174:177], v[198:201], v[118:121]
	v_mfma_f32_16x16x32_bf16 v[118:121], v[178:181], v[202:205], v[118:121]
	v_mfma_f32_16x16x32_bf16 v[114:117], v[182:185], v[198:201], v[114:117]
	v_mfma_f32_16x16x32_bf16 v[114:117], v[186:189], v[202:205], v[114:117]
	v_mfma_f32_16x16x32_bf16 v[110:113], v[174:177], v[206:209], v[110:113]
	v_mfma_f32_16x16x32_bf16 v[110:113], v[178:181], v[210:213], v[110:113]
	v_mfma_f32_16x16x32_bf16 v[106:109], v[182:185], v[206:209], v[106:109]
	v_mfma_f32_16x16x32_bf16 v[106:109], v[186:189], v[210:213], v[106:109]
	v_mfma_f32_16x16x32_bf16 v[102:105], v[174:177], v[214:217], v[102:105]
	v_mfma_f32_16x16x32_bf16 v[102:105], v[178:181], v[218:221], v[102:105]
	v_mfma_f32_16x16x32_bf16 v[98:101], v[182:185], v[214:217], v[98:101]
	v_mfma_f32_16x16x32_bf16 v[98:101], v[186:189], v[218:221], v[98:101]
	s_barrier
	s_add_i32 s81, s62, s38
	s_mov_b32 m0, s81
	s_nop 0
	global_load_lds_dwordx4 v138, s[34:35]
	s_add_i32 m0, s81, 0x2000
	s_add_u32 s86, s34, 0x100000
	s_addc_u32 s87, s35, 0
	s_add_i32 s81, s63, s38
	global_load_lds_dwordx4 v134, s[34:35]
	s_mov_b32 m0, s81
	s_nop 0
	global_load_lds_dwordx4 v138, s[86:87]
	s_add_i32 m0, s81, 0x2000
	s_nop 0
	global_load_lds_dwordx4 v134, s[86:87]
	s_mov_b32 m0, s42
	s_nop 0
	global_load_lds_dwordx4 v140, s[36:37]
	s_mov_b32 m0, s43
	s_nop 0
	global_load_lds_dwordx4 v136, s[36:37]
	ds_read_b128 v[190:193], v161 offset:16384
	ds_read_b128 v[194:197], v161 offset:17408
	ds_read_b128 v[198:201], v161 offset:18432
	ds_read_b128 v[202:205], v161 offset:19456
	ds_read_b128 v[206:209], v161 offset:20480
	ds_read_b128 v[210:213], v161 offset:21504
	ds_read_b128 v[214:217], v161 offset:22528
	ds_read_b128 v[218:221], v161 offset:23552
	s_waitcnt vmcnt(8)
	s_waitcnt lgkmcnt(0)
	s_barrier
	s_waitcnt lgkmcnt(0)
	v_mfma_f32_16x16x32_bf16 v[30:33], v[130:133], v[190:193], v[30:33]
	v_mfma_f32_16x16x32_bf16 v[30:33], v[162:165], v[194:197], v[30:33]
	v_mfma_f32_16x16x32_bf16 v[26:29], v[166:169], v[190:193], v[26:29]
	v_mfma_f32_16x16x32_bf16 v[26:29], v[170:173], v[194:197], v[26:29]
	v_mfma_f32_16x16x32_bf16 v[22:25], v[130:133], v[198:201], v[22:25]
	v_mfma_f32_16x16x32_bf16 v[22:25], v[162:165], v[202:205], v[22:25]
	v_mfma_f32_16x16x32_bf16 v[18:21], v[166:169], v[198:201], v[18:21]
	v_mfma_f32_16x16x32_bf16 v[18:21], v[170:173], v[202:205], v[18:21]
	v_mfma_f32_16x16x32_bf16 v[14:17], v[130:133], v[206:209], v[14:17]
	v_mfma_f32_16x16x32_bf16 v[14:17], v[162:165], v[210:213], v[14:17]
	v_mfma_f32_16x16x32_bf16 v[10:13], v[166:169], v[206:209], v[10:13]
	v_mfma_f32_16x16x32_bf16 v[10:13], v[170:173], v[210:213], v[10:13]
	v_mfma_f32_16x16x32_bf16 v[6:9], v[130:133], v[214:217], v[6:9]
	v_mfma_f32_16x16x32_bf16 v[6:9], v[162:165], v[218:221], v[6:9]
	v_mfma_f32_16x16x32_bf16 v[2:5], v[166:169], v[214:217], v[2:5]
	v_mfma_f32_16x16x32_bf16 v[2:5], v[170:173], v[218:221], v[2:5]
	v_mfma_f32_16x16x32_bf16 v[94:97], v[174:177], v[190:193], v[94:97]
	v_mfma_f32_16x16x32_bf16 v[94:97], v[178:181], v[194:197], v[94:97]
	v_mfma_f32_16x16x32_bf16 v[90:93], v[182:185], v[190:193], v[90:93]
	v_mfma_f32_16x16x32_bf16 v[90:93], v[186:189], v[194:197], v[90:93]
	v_mfma_f32_16x16x32_bf16 v[86:89], v[174:177], v[198:201], v[86:89]
	v_mfma_f32_16x16x32_bf16 v[86:89], v[178:181], v[202:205], v[86:89]
	v_mfma_f32_16x16x32_bf16 v[82:85], v[182:185], v[198:201], v[82:85]
	v_mfma_f32_16x16x32_bf16 v[82:85], v[186:189], v[202:205], v[82:85]
	v_mfma_f32_16x16x32_bf16 v[78:81], v[174:177], v[206:209], v[78:81]
	v_mfma_f32_16x16x32_bf16 v[78:81], v[178:181], v[210:213], v[78:81]
	v_mfma_f32_16x16x32_bf16 v[74:77], v[182:185], v[206:209], v[74:77]
	v_mfma_f32_16x16x32_bf16 v[74:77], v[186:189], v[210:213], v[74:77]
	v_mfma_f32_16x16x32_bf16 v[70:73], v[174:177], v[214:217], v[70:73]
	v_mfma_f32_16x16x32_bf16 v[70:73], v[178:181], v[218:221], v[70:73]
	v_mfma_f32_16x16x32_bf16 v[66:69], v[182:185], v[214:217], v[66:69]
	v_mfma_f32_16x16x32_bf16 v[66:69], v[186:189], v[218:221], v[66:69]
	s_barrier
	s_add_i32 s81, 0, 0x18000
	s_add_i32 s83, 0, 0x1c000
	s_add_u32 s36, s36, 0x100000
	s_addc_u32 s37, s37, 0
	s_mov_b32 m0, s46
	s_nop 0
	global_load_lds_dwordx4 v140, s[36:37]
	s_mov_b32 m0, s47
	s_nop 0
	global_load_lds_dwordx4 v136, s[36:37]
	v_add_u32_e32 v154, s81, v157
	ds_read_b128 v[130:133], v154
	ds_read_b128 v[162:165], v154 offset:1024
	ds_read_b128 v[166:169], v154 offset:2048
	ds_read_b128 v[170:173], v154 offset:3072
	v_add_u32_e32 v154, s83, v157
	ds_read_b128 v[174:177], v154
	ds_read_b128 v[178:181], v154 offset:1024
	ds_read_b128 v[182:185], v154 offset:2048
	ds_read_b128 v[186:189], v154 offset:3072
	ds_read_b128 v[190:193], v161 offset:32768
	ds_read_b128 v[194:197], v161 offset:33792
	ds_read_b128 v[198:201], v161 offset:34816
	ds_read_b128 v[202:205], v161 offset:35840
	ds_read_b128 v[206:209], v161 offset:36864
	ds_read_b128 v[210:213], v161 offset:37888
	ds_read_b128 v[214:217], v161 offset:38912
	ds_read_b128 v[218:221], v161 offset:39936
	s_waitcnt vmcnt(8)
	s_waitcnt lgkmcnt(0)
	s_barrier
	s_waitcnt lgkmcnt(0)
	v_mfma_f32_16x16x32_bf16 v[62:65], v[130:133], v[190:193], v[62:65]
	v_mfma_f32_16x16x32_bf16 v[62:65], v[162:165], v[194:197], v[62:65]
	v_mfma_f32_16x16x32_bf16 v[58:61], v[166:169], v[190:193], v[58:61]
	v_mfma_f32_16x16x32_bf16 v[58:61], v[170:173], v[194:197], v[58:61]
	v_mfma_f32_16x16x32_bf16 v[54:57], v[130:133], v[198:201], v[54:57]
	v_mfma_f32_16x16x32_bf16 v[54:57], v[162:165], v[202:205], v[54:57]
	v_mfma_f32_16x16x32_bf16 v[50:53], v[166:169], v[198:201], v[50:53]
	v_mfma_f32_16x16x32_bf16 v[50:53], v[170:173], v[202:205], v[50:53]
	v_mfma_f32_16x16x32_bf16 v[46:49], v[130:133], v[206:209], v[46:49]
	v_mfma_f32_16x16x32_bf16 v[46:49], v[162:165], v[210:213], v[46:49]
	v_mfma_f32_16x16x32_bf16 v[42:45], v[166:169], v[206:209], v[42:45]
	v_mfma_f32_16x16x32_bf16 v[42:45], v[170:173], v[210:213], v[42:45]
	v_mfma_f32_16x16x32_bf16 v[38:41], v[130:133], v[214:217], v[38:41]
	v_mfma_f32_16x16x32_bf16 v[38:41], v[162:165], v[218:221], v[38:41]
	v_mfma_f32_16x16x32_bf16 v[34:37], v[166:169], v[214:217], v[34:37]
	v_mfma_f32_16x16x32_bf16 v[34:37], v[170:173], v[218:221], v[34:37]
	v_mfma_f32_16x16x32_bf16 v[126:129], v[174:177], v[190:193], v[126:129]
	v_mfma_f32_16x16x32_bf16 v[126:129], v[178:181], v[194:197], v[126:129]
	v_mfma_f32_16x16x32_bf16 v[122:125], v[182:185], v[190:193], v[122:125]
	v_mfma_f32_16x16x32_bf16 v[122:125], v[186:189], v[194:197], v[122:125]
	v_mfma_f32_16x16x32_bf16 v[118:121], v[174:177], v[198:201], v[118:121]
	v_mfma_f32_16x16x32_bf16 v[118:121], v[178:181], v[202:205], v[118:121]
	v_mfma_f32_16x16x32_bf16 v[114:117], v[182:185], v[198:201], v[114:117]
	v_mfma_f32_16x16x32_bf16 v[114:117], v[186:189], v[202:205], v[114:117]
	v_mfma_f32_16x16x32_bf16 v[110:113], v[174:177], v[206:209], v[110:113]
	v_mfma_f32_16x16x32_bf16 v[110:113], v[178:181], v[210:213], v[110:113]
	v_mfma_f32_16x16x32_bf16 v[106:109], v[182:185], v[206:209], v[106:109]
	v_mfma_f32_16x16x32_bf16 v[106:109], v[186:189], v[210:213], v[106:109]
	v_mfma_f32_16x16x32_bf16 v[102:105], v[174:177], v[214:217], v[102:105]
	v_mfma_f32_16x16x32_bf16 v[102:105], v[178:181], v[218:221], v[102:105]
	v_mfma_f32_16x16x32_bf16 v[98:101], v[182:185], v[214:217], v[98:101]
	v_mfma_f32_16x16x32_bf16 v[98:101], v[186:189], v[218:221], v[98:101]
	s_barrier
	s_add_u32 s36, s34, 0x4000
	s_addc_u32 s37, s35, 0
	s_add_i32 s81, s81, s38
	s_mov_b32 m0, s81
	s_nop 0
	global_load_lds_dwordx4 v138, s[36:37]
	s_add_i32 m0, s81, 0x2000
	s_add_u32 s34, s34, 0x104000
	s_addc_u32 s35, s35, 0
	global_load_lds_dwordx4 v134, s[36:37]
	s_add_i32 s36, s83, s38
	s_mov_b32 m0, s36
	s_nop 0
	global_load_lds_dwordx4 v138, s[34:35]
	s_add_i32 m0, s36, 0x2000
	s_nop 0
	global_load_lds_dwordx4 v134, s[34:35]
	s_mov_b32 m0, s58
	s_nop 0
	global_load_lds_dwordx4 v140, s[30:31]
	s_mov_b32 m0, s59
	s_nop 0
	global_load_lds_dwordx4 v136, s[30:31]
	ds_read_b128 v[190:193], v161 offset:49152
	ds_read_b128 v[194:197], v161 offset:50176
	ds_read_b128 v[198:201], v161 offset:51200
	ds_read_b128 v[202:205], v161 offset:52224
	ds_read_b128 v[206:209], v161 offset:53248
	ds_read_b128 v[210:213], v161 offset:54272
	ds_read_b128 v[214:217], v161 offset:55296
	ds_read_b128 v[218:221], v161 offset:56320
	s_waitcnt vmcnt(8)
	s_waitcnt lgkmcnt(0)
	s_barrier
	s_waitcnt lgkmcnt(0)
	v_mfma_f32_16x16x32_bf16 v[30:33], v[130:133], v[190:193], v[30:33]
	v_mfma_f32_16x16x32_bf16 v[30:33], v[162:165], v[194:197], v[30:33]
	v_mfma_f32_16x16x32_bf16 v[26:29], v[166:169], v[190:193], v[26:29]
	v_mfma_f32_16x16x32_bf16 v[26:29], v[170:173], v[194:197], v[26:29]
	v_mfma_f32_16x16x32_bf16 v[22:25], v[130:133], v[198:201], v[22:25]
	v_mfma_f32_16x16x32_bf16 v[22:25], v[162:165], v[202:205], v[22:25]
	v_mfma_f32_16x16x32_bf16 v[18:21], v[166:169], v[198:201], v[18:21]
	v_mfma_f32_16x16x32_bf16 v[18:21], v[170:173], v[202:205], v[18:21]
	v_mfma_f32_16x16x32_bf16 v[14:17], v[130:133], v[206:209], v[14:17]
	v_mfma_f32_16x16x32_bf16 v[14:17], v[162:165], v[210:213], v[14:17]
	v_mfma_f32_16x16x32_bf16 v[10:13], v[166:169], v[206:209], v[10:13]
	v_mfma_f32_16x16x32_bf16 v[10:13], v[170:173], v[210:213], v[10:13]
	v_mfma_f32_16x16x32_bf16 v[6:9], v[130:133], v[214:217], v[6:9]
	v_mfma_f32_16x16x32_bf16 v[6:9], v[162:165], v[218:221], v[6:9]
	v_mfma_f32_16x16x32_bf16 v[2:5], v[166:169], v[214:217], v[2:5]
	v_mfma_f32_16x16x32_bf16 v[2:5], v[170:173], v[218:221], v[2:5]
	v_mfma_f32_16x16x32_bf16 v[94:97], v[174:177], v[190:193], v[94:97]
	v_mfma_f32_16x16x32_bf16 v[94:97], v[178:181], v[194:197], v[94:97]
	v_mfma_f32_16x16x32_bf16 v[90:93], v[182:185], v[190:193], v[90:93]
	v_mfma_f32_16x16x32_bf16 v[90:93], v[186:189], v[194:197], v[90:93]
	v_mfma_f32_16x16x32_bf16 v[86:89], v[174:177], v[198:201], v[86:89]
	v_mfma_f32_16x16x32_bf16 v[86:89], v[178:181], v[202:205], v[86:89]
	v_mfma_f32_16x16x32_bf16 v[82:85], v[182:185], v[198:201], v[82:85]
	v_mfma_f32_16x16x32_bf16 v[82:85], v[186:189], v[202:205], v[82:85]
	v_mfma_f32_16x16x32_bf16 v[78:81], v[174:177], v[206:209], v[78:81]
	v_mfma_f32_16x16x32_bf16 v[78:81], v[178:181], v[210:213], v[78:81]
	v_mfma_f32_16x16x32_bf16 v[74:77], v[182:185], v[206:209], v[74:77]
	v_mfma_f32_16x16x32_bf16 v[74:77], v[186:189], v[210:213], v[74:77]
	v_mfma_f32_16x16x32_bf16 v[70:73], v[174:177], v[214:217], v[70:73]
	v_mfma_f32_16x16x32_bf16 v[70:73], v[178:181], v[218:221], v[70:73]
	v_mfma_f32_16x16x32_bf16 v[66:69], v[182:185], v[214:217], v[66:69]
	v_mfma_f32_16x16x32_bf16 v[66:69], v[186:189], v[218:221], v[66:69]
	s_barrier
	s_add_i32 s80, s80, 2
	s_add_u32 s26, s26, 0x8000
	s_addc_u32 s27, s27, 0
	s_add_u32 s78, s78, 0x8000
	s_addc_u32 s79, s79, 0
	s_cmp_gt_u32 s80, 61
	s_cbranch_scc0 .LBB0_536
	s_and_b64 vcc, exec, s[14:15]
	s_cbranch_vccz .LBB0_539
	s_barrier

.LBB0_1005:
	s_add_i32 s70, s31, 2
	s_add_u32 s26, s24, 0xfff44000
	s_addc_u32 s27, s25, -1
	s_cmp_eq_u32 s67, s31
	s_cselect_b32 s34, s6, s26
	s_cselect_b32 s35, s7, s27
	s_cselect_b32 s30, s20, s68
	s_cselect_b32 s31, s21, s69
	s_add_u32 s26, s34, 0x4000
	s_addc_u32 s27, s35, 0
	s_add_i32 m0, s37, 0xc000
	s_nop 0
	global_load_lds_dwordx4 v190, s[24:25]
	s_add_i32 m0, s37, 0xe000
	s_nop 0
	global_load_lds_dwordx4 v192, s[24:25]
	v_add_u32_e32 v142, s46, v200
	v_add_u32_e32 v158, s47, v200
	ds_read_b128 v[130:133], v142
	ds_read_b128 v[134:137], v142 offset:1024
	ds_read_b128 v[138:141], v142 offset:2048
	ds_read_b128 v[142:145], v142 offset:3072
	ds_read_b128 v[146:149], v158
	ds_read_b128 v[150:153], v158 offset:1024
	ds_read_b128 v[154:157], v158 offset:2048
	ds_read_b128 v[158:161], v158 offset:3072
	ds_read_b128 v[162:165], v201
	ds_read_b128 v[166:169], v201 offset:1024
	ds_read_b128 v[170:173], v201 offset:2048
	ds_read_b128 v[174:177], v201 offset:3072
	ds_read_b128 v[202:205], v201 offset:4096
	ds_read_b128 v[206:209], v201 offset:5120
	ds_read_b128 v[210:213], v201 offset:6144
	ds_read_b128 v[214:217], v201 offset:7168
	s_waitcnt vmcnt(8)
	s_waitcnt lgkmcnt(0)
	s_barrier
	s_waitcnt lgkmcnt(0)
	v_mfma_f32_16x16x32_bf16 v[126:129], v[130:133], v[162:165], v[126:129]
	v_mfma_f32_16x16x32_bf16 v[126:129], v[134:137], v[166:169], v[126:129]
	v_mfma_f32_16x16x32_bf16 v[122:125], v[138:141], v[162:165], v[122:125]
	v_mfma_f32_16x16x32_bf16 v[122:125], v[142:145], v[166:169], v[122:125]
	v_mfma_f32_16x16x32_bf16 v[118:121], v[130:133], v[170:173], v[118:121]
	v_mfma_f32_16x16x32_bf16 v[118:121], v[134:137], v[174:177], v[118:121]
	v_mfma_f32_16x16x32_bf16 v[114:117], v[138:141], v[170:173], v[114:117]
	v_mfma_f32_16x16x32_bf16 v[114:117], v[142:145], v[174:177], v[114:117]
	v_mfma_f32_16x16x32_bf16 v[110:113], v[130:133], v[202:205], v[110:113]
	v_mfma_f32_16x16x32_bf16 v[110:113], v[134:137], v[206:209], v[110:113]
	v_mfma_f32_16x16x32_bf16 v[106:109], v[138:141], v[202:205], v[106:109]
	v_mfma_f32_16x16x32_bf16 v[106:109], v[142:145], v[206:209], v[106:109]
	v_mfma_f32_16x16x32_bf16 v[102:105], v[130:133], v[210:213], v[102:105]
	v_mfma_f32_16x16x32_bf16 v[102:105], v[134:137], v[214:217], v[102:105]
	v_mfma_f32_16x16x32_bf16 v[98:101], v[138:141], v[210:213], v[98:101]
	v_mfma_f32_16x16x32_bf16 v[98:101], v[142:145], v[214:217], v[98:101]
	v_mfma_f32_16x16x32_bf16 v[94:97], v[146:149], v[162:165], v[94:97]
	v_mfma_f32_16x16x32_bf16 v[94:97], v[150:153], v[166:169], v[94:97]
	v_mfma_f32_16x16x32_bf16 v[90:93], v[154:157], v[162:165], v[90:93]
	v_mfma_f32_16x16x32_bf16 v[90:93], v[158:161], v[166:169], v[90:93]
	v_mfma_f32_16x16x32_bf16 v[86:89], v[146:149], v[170:173], v[86:89]
	v_mfma_f32_16x16x32_bf16 v[86:89], v[150:153], v[174:177], v[86:89]
	v_mfma_f32_16x16x32_bf16 v[82:85], v[154:157], v[170:173], v[82:85]
	v_mfma_f32_16x16x32_bf16 v[82:85], v[158:161], v[174:177], v[82:85]
	v_mfma_f32_16x16x32_bf16 v[78:81], v[146:149], v[202:205], v[78:81]
	v_mfma_f32_16x16x32_bf16 v[78:81], v[150:153], v[206:209], v[78:81]
	v_mfma_f32_16x16x32_bf16 v[74:77], v[154:157], v[202:205], v[74:77]
	v_mfma_f32_16x16x32_bf16 v[74:77], v[158:161], v[206:209], v[74:77]
	v_mfma_f32_16x16x32_bf16 v[66:69], v[146:149], v[210:213], v[66:69]
	v_mfma_f32_16x16x32_bf16 v[66:69], v[150:153], v[214:217], v[66:69]
	v_mfma_f32_16x16x32_bf16 v[58:61], v[154:157], v[210:213], v[58:61]
	v_mfma_f32_16x16x32_bf16 v[58:61], v[158:161], v[214:217], v[58:61]
	s_barrier
	s_add_i32 s71, s46, s36
	s_mov_b32 m0, s71
	s_nop 0
	global_load_lds_dwordx4 v182, s[30:31]
	s_add_i32 m0, s71, 0x2000
	s_add_u32 s72, s30, 0xc0000
	s_addc_u32 s73, s31, 0
	s_add_i32 s71, s47, s36
	global_load_lds_dwordx4 v178, s[30:31]
	s_mov_b32 m0, s71
	s_nop 0
	global_load_lds_dwordx4 v182, s[72:73]
	s_add_i32 m0, s71, 0x2000
	s_nop 0
	global_load_lds_dwordx4 v178, s[72:73]
	s_mov_b32 m0, s37
	s_nop 0
	global_load_lds_dwordx4 v184, s[34:35]
	s_mov_b32 m0, s38
	s_nop 0
	global_load_lds_dwordx4 v180, s[34:35]
	ds_read_b128 v[162:165], v201 offset:16384
	ds_read_b128 v[166:169], v201 offset:17408
	ds_read_b128 v[170:173], v201 offset:18432
	ds_read_b128 v[174:177], v201 offset:19456
	ds_read_b128 v[202:205], v201 offset:20480
	ds_read_b128 v[206:209], v201 offset:21504
	ds_read_b128 v[210:213], v201 offset:22528
	ds_read_b128 v[214:217], v201 offset:23552
	s_waitcnt vmcnt(8)
	s_waitcnt lgkmcnt(0)
	s_barrier
	s_waitcnt lgkmcnt(0)
	v_mfma_f32_16x16x32_bf16 v[70:73], v[130:133], v[162:165], v[70:73]
	v_mfma_f32_16x16x32_bf16 v[70:73], v[134:137], v[166:169], v[70:73]
	v_mfma_f32_16x16x32_bf16 v[62:65], v[138:141], v[162:165], v[62:65]
	v_mfma_f32_16x16x32_bf16 v[62:65], v[142:145], v[166:169], v[62:65]
	v_mfma_f32_16x16x32_bf16 v[54:57], v[130:133], v[170:173], v[54:57]
	v_mfma_f32_16x16x32_bf16 v[54:57], v[134:137], v[174:177], v[54:57]
	v_mfma_f32_16x16x32_bf16 v[50:53], v[138:141], v[170:173], v[50:53]
	v_mfma_f32_16x16x32_bf16 v[50:53], v[142:145], v[174:177], v[50:53]
	v_mfma_f32_16x16x32_bf16 v[46:49], v[130:133], v[202:205], v[46:49]
	v_mfma_f32_16x16x32_bf16 v[46:49], v[134:137], v[206:209], v[46:49]
	v_mfma_f32_16x16x32_bf16 v[42:45], v[138:141], v[202:205], v[42:45]
	v_mfma_f32_16x16x32_bf16 v[42:45], v[142:145], v[206:209], v[42:45]
	v_mfma_f32_16x16x32_bf16 v[38:41], v[130:133], v[210:213], v[38:41]
	v_mfma_f32_16x16x32_bf16 v[38:41], v[134:137], v[214:217], v[38:41]
	v_mfma_f32_16x16x32_bf16 v[34:37], v[138:141], v[210:213], v[34:37]
	v_mfma_f32_16x16x32_bf16 v[34:37], v[142:145], v[214:217], v[34:37]
	v_mfma_f32_16x16x32_bf16 v[30:33], v[146:149], v[162:165], v[30:33]
	v_mfma_f32_16x16x32_bf16 v[30:33], v[150:153], v[166:169], v[30:33]
	v_mfma_f32_16x16x32_bf16 v[26:29], v[154:157], v[162:165], v[26:29]
	v_mfma_f32_16x16x32_bf16 v[26:29], v[158:161], v[166:169], v[26:29]
	v_mfma_f32_16x16x32_bf16 v[22:25], v[146:149], v[170:173], v[22:25]
	v_mfma_f32_16x16x32_bf16 v[22:25], v[150:153], v[174:177], v[22:25]
	v_mfma_f32_16x16x32_bf16 v[18:21], v[154:157], v[170:173], v[18:21]
	v_mfma_f32_16x16x32_bf16 v[18:21], v[158:161], v[174:177], v[18:21]
	v_mfma_f32_16x16x32_bf16 v[14:17], v[146:149], v[202:205], v[14:17]
	v_mfma_f32_16x16x32_bf16 v[14:17], v[150:153], v[206:209], v[14:17]
	v_mfma_f32_16x16x32_bf16 v[10:13], v[154:157], v[202:205], v[10:13]
	v_mfma_f32_16x16x32_bf16 v[10:13], v[158:161], v[206:209], v[10:13]
	v_mfma_f32_16x16x32_bf16 v[6:9], v[146:149], v[210:213], v[6:9]
	v_mfma_f32_16x16x32_bf16 v[6:9], v[150:153], v[214:217], v[6:9]
	v_mfma_f32_16x16x32_bf16 v[2:5], v[154:157], v[210:213], v[2:5]
	v_mfma_f32_16x16x32_bf16 v[2:5], v[158:161], v[214:217], v[2:5]
	s_barrier
	s_add_i32 s71, 0, 0x18000
	s_add_i32 s72, 0, 0x1c000
	s_add_u32 s34, s34, 0xc0000
	s_addc_u32 s35, s35, 0
	s_mov_b32 m0, s39
	s_nop 0
	global_load_lds_dwordx4 v184, s[34:35]
	s_mov_b32 m0, s40
	s_nop 0
	global_load_lds_dwordx4 v180, s[34:35]
	v_add_u32_e32 v142, s71, v200
	v_add_u32_e32 v158, s72, v200
	ds_read_b128 v[130:133], v142
	ds_read_b128 v[134:137], v142 offset:1024
	ds_read_b128 v[138:141], v142 offset:2048
	ds_read_b128 v[142:145], v142 offset:3072
	ds_read_b128 v[146:149], v158
	ds_read_b128 v[150:153], v158 offset:1024
	ds_read_b128 v[154:157], v158 offset:2048
	ds_read_b128 v[158:161], v158 offset:3072
	ds_read_b128 v[162:165], v201 offset:32768
	ds_read_b128 v[166:169], v201 offset:33792
	ds_read_b128 v[170:173], v201 offset:34816
	ds_read_b128 v[174:177], v201 offset:35840
	ds_read_b128 v[202:205], v201 offset:36864
	ds_read_b128 v[206:209], v201 offset:37888
	ds_read_b128 v[210:213], v201 offset:38912
	ds_read_b128 v[214:217], v201 offset:39936
	s_waitcnt vmcnt(8)
	s_waitcnt lgkmcnt(0)
	s_barrier
	s_waitcnt lgkmcnt(0)
	v_mfma_f32_16x16x32_bf16 v[126:129], v[130:133], v[162:165], v[126:129]
	v_mfma_f32_16x16x32_bf16 v[126:129], v[134:137], v[166:169], v[126:129]
	v_mfma_f32_16x16x32_bf16 v[122:125], v[138:141], v[162:165], v[122:125]
	v_mfma_f32_16x16x32_bf16 v[122:125], v[142:145], v[166:169], v[122:125]
	v_mfma_f32_16x16x32_bf16 v[118:121], v[130:133], v[170:173], v[118:121]
	v_mfma_f32_16x16x32_bf16 v[118:121], v[134:137], v[174:177], v[118:121]
	v_mfma_f32_16x16x32_bf16 v[114:117], v[138:141], v[170:173], v[114:117]
	v_mfma_f32_16x16x32_bf16 v[114:117], v[142:145], v[174:177], v[114:117]
	v_mfma_f32_16x16x32_bf16 v[110:113], v[130:133], v[202:205], v[110:113]
	v_mfma_f32_16x16x32_bf16 v[110:113], v[134:137], v[206:209], v[110:113]
	v_mfma_f32_16x16x32_bf16 v[106:109], v[138:141], v[202:205], v[106:109]
	v_mfma_f32_16x16x32_bf16 v[106:109], v[142:145], v[206:209], v[106:109]
	v_mfma_f32_16x16x32_bf16 v[102:105], v[130:133], v[210:213], v[102:105]
	v_mfma_f32_16x16x32_bf16 v[102:105], v[134:137], v[214:217], v[102:105]
	v_mfma_f32_16x16x32_bf16 v[98:101], v[138:141], v[210:213], v[98:101]
	v_mfma_f32_16x16x32_bf16 v[98:101], v[142:145], v[214:217], v[98:101]
	v_mfma_f32_16x16x32_bf16 v[94:97], v[146:149], v[162:165], v[94:97]
	v_mfma_f32_16x16x32_bf16 v[94:97], v[150:153], v[166:169], v[94:97]
	v_mfma_f32_16x16x32_bf16 v[90:93], v[154:157], v[162:165], v[90:93]
	v_mfma_f32_16x16x32_bf16 v[90:93], v[158:161], v[166:169], v[90:93]
	v_mfma_f32_16x16x32_bf16 v[86:89], v[146:149], v[170:173], v[86:89]
	v_mfma_f32_16x16x32_bf16 v[86:89], v[150:153], v[174:177], v[86:89]
	v_mfma_f32_16x16x32_bf16 v[82:85], v[154:157], v[170:173], v[82:85]
	v_mfma_f32_16x16x32_bf16 v[82:85], v[158:161], v[174:177], v[82:85]
	v_mfma_f32_16x16x32_bf16 v[78:81], v[146:149], v[202:205], v[78:81]
	v_mfma_f32_16x16x32_bf16 v[78:81], v[150:153], v[206:209], v[78:81]
	v_mfma_f32_16x16x32_bf16 v[74:77], v[154:157], v[202:205], v[74:77]
	v_mfma_f32_16x16x32_bf16 v[74:77], v[158:161], v[206:209], v[74:77]
	v_mfma_f32_16x16x32_bf16 v[66:69], v[146:149], v[210:213], v[66:69]
	v_mfma_f32_16x16x32_bf16 v[66:69], v[150:153], v[214:217], v[66:69]
	v_mfma_f32_16x16x32_bf16 v[58:61], v[154:157], v[210:213], v[58:61]
	v_mfma_f32_16x16x32_bf16 v[58:61], v[158:161], v[214:217], v[58:61]
	s_barrier
	s_add_u32 s34, s30, 0x4000
	s_addc_u32 s35, s31, 0
	s_add_i32 s71, s71, s36
	s_mov_b32 m0, s71
	s_nop 0
	global_load_lds_dwordx4 v182, s[34:35]
	s_add_i32 m0, s71, 0x2000
	s_add_u32 s30, s30, 0xc4000
	s_addc_u32 s31, s31, 0
	global_load_lds_dwordx4 v178, s[34:35]
	s_add_i32 s34, s72, s36
	s_mov_b32 m0, s34
	s_nop 0
	global_load_lds_dwordx4 v182, s[30:31]
	s_add_i32 m0, s34, 0x2000
	s_nop 0
	global_load_lds_dwordx4 v178, s[30:31]
	s_mov_b32 m0, s42
	s_nop 0
	global_load_lds_dwordx4 v184, s[26:27]
	s_mov_b32 m0, s43
	s_nop 0
	global_load_lds_dwordx4 v180, s[26:27]
	ds_read_b128 v[162:165], v201 offset:49152
	ds_read_b128 v[166:169], v201 offset:50176
	ds_read_b128 v[170:173], v201 offset:51200
	ds_read_b128 v[174:177], v201 offset:52224
	ds_read_b128 v[202:205], v201 offset:53248
	ds_read_b128 v[206:209], v201 offset:54272
	ds_read_b128 v[210:213], v201 offset:55296
	ds_read_b128 v[214:217], v201 offset:56320
	s_waitcnt vmcnt(8)
	s_waitcnt lgkmcnt(0)
	s_barrier
	s_waitcnt lgkmcnt(0)
	v_mfma_f32_16x16x32_bf16 v[70:73], v[130:133], v[162:165], v[70:73]
	v_mfma_f32_16x16x32_bf16 v[70:73], v[134:137], v[166:169], v[70:73]
	v_mfma_f32_16x16x32_bf16 v[62:65], v[138:141], v[162:165], v[62:65]
	v_mfma_f32_16x16x32_bf16 v[62:65], v[142:145], v[166:169], v[62:65]
	v_mfma_f32_16x16x32_bf16 v[54:57], v[130:133], v[170:173], v[54:57]
	v_mfma_f32_16x16x32_bf16 v[54:57], v[134:137], v[174:177], v[54:57]
	v_mfma_f32_16x16x32_bf16 v[50:53], v[138:141], v[170:173], v[50:53]
	v_mfma_f32_16x16x32_bf16 v[50:53], v[142:145], v[174:177], v[50:53]
	v_mfma_f32_16x16x32_bf16 v[46:49], v[130:133], v[202:205], v[46:49]
	v_mfma_f32_16x16x32_bf16 v[46:49], v[134:137], v[206:209], v[46:49]
	v_mfma_f32_16x16x32_bf16 v[42:45], v[138:141], v[202:205], v[42:45]
	v_mfma_f32_16x16x32_bf16 v[42:45], v[142:145], v[206:209], v[42:45]
	v_mfma_f32_16x16x32_bf16 v[38:41], v[130:133], v[210:213], v[38:41]
	v_mfma_f32_16x16x32_bf16 v[38:41], v[134:137], v[214:217], v[38:41]
	v_mfma_f32_16x16x32_bf16 v[34:37], v[138:141], v[210:213], v[34:37]
	v_mfma_f32_16x16x32_bf16 v[34:37], v[142:145], v[214:217], v[34:37]
	v_mfma_f32_16x16x32_bf16 v[30:33], v[146:149], v[162:165], v[30:33]
	v_mfma_f32_16x16x32_bf16 v[30:33], v[150:153], v[166:169], v[30:33]
	v_mfma_f32_16x16x32_bf16 v[26:29], v[154:157], v[162:165], v[26:29]
	v_mfma_f32_16x16x32_bf16 v[26:29], v[158:161], v[166:169], v[26:29]
	v_mfma_f32_16x16x32_bf16 v[22:25], v[146:149], v[170:173], v[22:25]
	v_mfma_f32_16x16x32_bf16 v[22:25], v[150:153], v[174:177], v[22:25]
	v_mfma_f32_16x16x32_bf16 v[18:21], v[154:157], v[170:173], v[18:21]
	v_mfma_f32_16x16x32_bf16 v[18:21], v[158:161], v[174:177], v[18:21]
	v_mfma_f32_16x16x32_bf16 v[14:17], v[146:149], v[202:205], v[14:17]
	v_mfma_f32_16x16x32_bf16 v[14:17], v[150:153], v[206:209], v[14:17]
	v_mfma_f32_16x16x32_bf16 v[10:13], v[154:157], v[202:205], v[10:13]
	v_mfma_f32_16x16x32_bf16 v[10:13], v[158:161], v[206:209], v[10:13]
	v_mfma_f32_16x16x32_bf16 v[6:9], v[146:149], v[210:213], v[6:9]
	v_mfma_f32_16x16x32_bf16 v[6:9], v[150:153], v[214:217], v[6:9]
	v_mfma_f32_16x16x32_bf16 v[2:5], v[154:157], v[210:213], v[2:5]
	v_mfma_f32_16x16x32_bf16 v[2:5], v[158:161], v[214:217], v[2:5]
	s_barrier
	s_add_u32 s24, s24, 0x8000
	s_addc_u32 s25, s25, 0
	s_add_u32 s68, s68, 0x8000
	s_addc_u32 s69, s69, 0
	s_cmp_ge_u32 s70, s66
	s_mov_b32 s31, s70
	s_cbranch_scc0 .LBB0_1005
	s_and_b64 vcc, exec, s[18:19]
	s_cbranch_vccnz .LBB0_1010
	v_lshl_add_u32 v162, s65, 8, v189
	s_mov_b64 s[24:25], -1
	s_and_b64 vcc, exec, s[22:23]
	s_cbranch_vccnz .LBB0_1011

.LBB0_1088:
	s_add_u32 s38, s36, 0xfff04000
	s_addc_u32 s39, s37, -1
	s_cmp_eq_u32 s72, 60
	s_cselect_b32 s42, s35, s38
	s_cselect_b32 s43, s25, s39
	s_cselect_b32 s40, s69, s70
	s_cselect_b32 s41, s23, s71
	s_add_u32 s38, s42, 0x4000
	s_addc_u32 s39, s43, 0
	s_add_i32 m0, s47, 0xc000
	s_nop 0
	global_load_lds_dwordx4 v188, s[36:37]
	s_add_i32 m0, s47, 0xe000
	s_nop 0
	global_load_lds_dwordx4 v190, s[36:37]
	ds_read_b128 v[130:133], v209
	ds_read_b128 v[134:137], v209 offset:1024
	ds_read_b128 v[138:141], v209 offset:2048
	ds_read_b128 v[142:145], v209 offset:3072
	ds_read_b128 v[146:149], v210
	ds_read_b128 v[150:153], v210 offset:1024
	ds_read_b128 v[154:157], v210 offset:2048
	ds_read_b128 v[158:161], v210 offset:3072
	ds_read_b128 v[162:165], v211
	ds_read_b128 v[166:169], v211 offset:1024
	ds_read_b128 v[170:173], v211 offset:2048
	ds_read_b128 v[174:177], v211 offset:3072
	ds_read_b128 v[196:199], v211 offset:4096
	ds_read_b128 v[200:203], v211 offset:5120
	ds_read_b128 v[214:217], v211 offset:6144
	ds_read_b128 v[218:221], v211 offset:7168
	s_waitcnt vmcnt(8)
	s_waitcnt lgkmcnt(0)
	s_barrier
	s_waitcnt lgkmcnt(0)
	v_mfma_f32_16x16x32_bf16 v[126:129], v[130:133], v[162:165], v[126:129]
	v_mfma_f32_16x16x32_bf16 v[126:129], v[134:137], v[166:169], v[126:129]
	v_mfma_f32_16x16x32_bf16 v[122:125], v[138:141], v[162:165], v[122:125]
	v_mfma_f32_16x16x32_bf16 v[122:125], v[142:145], v[166:169], v[122:125]
	v_mfma_f32_16x16x32_bf16 v[110:113], v[130:133], v[170:173], v[110:113]
	v_mfma_f32_16x16x32_bf16 v[110:113], v[134:137], v[174:177], v[110:113]
	v_mfma_f32_16x16x32_bf16 v[106:109], v[138:141], v[170:173], v[106:109]
	v_mfma_f32_16x16x32_bf16 v[106:109], v[142:145], v[174:177], v[106:109]
	v_mfma_f32_16x16x32_bf16 v[94:97], v[130:133], v[196:199], v[94:97]
	v_mfma_f32_16x16x32_bf16 v[94:97], v[134:137], v[200:203], v[94:97]
	v_mfma_f32_16x16x32_bf16 v[90:93], v[138:141], v[196:199], v[90:93]
	v_mfma_f32_16x16x32_bf16 v[90:93], v[142:145], v[200:203], v[90:93]
	v_mfma_f32_16x16x32_bf16 v[78:81], v[130:133], v[214:217], v[78:81]
	v_mfma_f32_16x16x32_bf16 v[78:81], v[134:137], v[218:221], v[78:81]
	v_mfma_f32_16x16x32_bf16 v[74:77], v[138:141], v[214:217], v[74:77]
	v_mfma_f32_16x16x32_bf16 v[74:77], v[142:145], v[218:221], v[74:77]
	v_mfma_f32_16x16x32_bf16 v[118:121], v[146:149], v[162:165], v[118:121]
	v_mfma_f32_16x16x32_bf16 v[118:121], v[150:153], v[166:169], v[118:121]
	v_mfma_f32_16x16x32_bf16 v[114:117], v[154:157], v[162:165], v[114:117]
	v_mfma_f32_16x16x32_bf16 v[114:117], v[158:161], v[166:169], v[114:117]
	v_mfma_f32_16x16x32_bf16 v[102:105], v[146:149], v[170:173], v[102:105]
	v_mfma_f32_16x16x32_bf16 v[102:105], v[150:153], v[174:177], v[102:105]
	v_mfma_f32_16x16x32_bf16 v[98:101], v[154:157], v[170:173], v[98:101]
	v_mfma_f32_16x16x32_bf16 v[98:101], v[158:161], v[174:177], v[98:101]
	v_mfma_f32_16x16x32_bf16 v[86:89], v[146:149], v[196:199], v[86:89]
	v_mfma_f32_16x16x32_bf16 v[86:89], v[150:153], v[200:203], v[86:89]
	v_mfma_f32_16x16x32_bf16 v[82:85], v[154:157], v[196:199], v[82:85]
	v_mfma_f32_16x16x32_bf16 v[82:85], v[158:161], v[200:203], v[82:85]
	v_mfma_f32_16x16x32_bf16 v[70:73], v[146:149], v[214:217], v[70:73]
	v_mfma_f32_16x16x32_bf16 v[70:73], v[150:153], v[218:221], v[70:73]
	v_mfma_f32_16x16x32_bf16 v[66:69], v[154:157], v[214:217], v[66:69]
	v_mfma_f32_16x16x32_bf16 v[66:69], v[158:161], v[218:221], v[66:69]
	s_barrier
	s_add_i32 s73, s66, s46
	s_mov_b32 m0, s73
	s_nop 0
	global_load_lds_dwordx4 v180, s[40:41]
	s_add_i32 m0, s73, 0x2000
	s_add_u32 s74, s40, 0x100000
	s_addc_u32 s75, s41, 0
	s_add_i32 s73, s67, s46
	global_load_lds_dwordx4 v184, s[40:41]
	s_mov_b32 m0, s73
	s_nop 0
	global_load_lds_dwordx4 v180, s[74:75]
	s_add_i32 m0, s73, 0x2000
	s_nop 0
	global_load_lds_dwordx4 v184, s[74:75]
	s_mov_b32 m0, s47
	s_nop 0
	global_load_lds_dwordx4 v178, s[42:43]
	s_mov_b32 m0, s59
	s_nop 0
	global_load_lds_dwordx4 v182, s[42:43]
	ds_read_b128 v[162:165], v211 offset:16384
	ds_read_b128 v[166:169], v211 offset:17408
	ds_read_b128 v[170:173], v211 offset:18432
	ds_read_b128 v[174:177], v211 offset:19456
	ds_read_b128 v[196:199], v211 offset:20480
	ds_read_b128 v[200:203], v211 offset:21504
	ds_read_b128 v[214:217], v211 offset:22528
	ds_read_b128 v[218:221], v211 offset:23552
	s_waitcnt vmcnt(8)
	s_waitcnt lgkmcnt(0)
	s_barrier
	s_waitcnt lgkmcnt(0)
	v_mfma_f32_16x16x32_bf16 v[62:65], v[130:133], v[162:165], v[62:65]
	v_mfma_f32_16x16x32_bf16 v[62:65], v[134:137], v[166:169], v[62:65]
	v_mfma_f32_16x16x32_bf16 v[58:61], v[138:141], v[162:165], v[58:61]
	v_mfma_f32_16x16x32_bf16 v[58:61], v[142:145], v[166:169], v[58:61]
	v_mfma_f32_16x16x32_bf16 v[46:49], v[130:133], v[170:173], v[46:49]
	v_mfma_f32_16x16x32_bf16 v[46:49], v[134:137], v[174:177], v[46:49]
	v_mfma_f32_16x16x32_bf16 v[42:45], v[138:141], v[170:173], v[42:45]
	v_mfma_f32_16x16x32_bf16 v[42:45], v[142:145], v[174:177], v[42:45]
	v_mfma_f32_16x16x32_bf16 v[30:33], v[130:133], v[196:199], v[30:33]
	v_mfma_f32_16x16x32_bf16 v[30:33], v[134:137], v[200:203], v[30:33]
	v_mfma_f32_16x16x32_bf16 v[26:29], v[138:141], v[196:199], v[26:29]
	v_mfma_f32_16x16x32_bf16 v[26:29], v[142:145], v[200:203], v[26:29]
	v_mfma_f32_16x16x32_bf16 v[14:17], v[130:133], v[214:217], v[14:17]
	v_mfma_f32_16x16x32_bf16 v[14:17], v[134:137], v[218:221], v[14:17]
	v_mfma_f32_16x16x32_bf16 v[10:13], v[138:141], v[214:217], v[10:13]
	v_mfma_f32_16x16x32_bf16 v[10:13], v[142:145], v[218:221], v[10:13]
	v_mfma_f32_16x16x32_bf16 v[54:57], v[146:149], v[162:165], v[54:57]
	v_mfma_f32_16x16x32_bf16 v[54:57], v[150:153], v[166:169], v[54:57]
	v_mfma_f32_16x16x32_bf16 v[50:53], v[154:157], v[162:165], v[50:53]
	v_mfma_f32_16x16x32_bf16 v[50:53], v[158:161], v[166:169], v[50:53]
	v_mfma_f32_16x16x32_bf16 v[38:41], v[146:149], v[170:173], v[38:41]
	v_mfma_f32_16x16x32_bf16 v[38:41], v[150:153], v[174:177], v[38:41]
	v_mfma_f32_16x16x32_bf16 v[34:37], v[154:157], v[170:173], v[34:37]
	v_mfma_f32_16x16x32_bf16 v[34:37], v[158:161], v[174:177], v[34:37]
	v_mfma_f32_16x16x32_bf16 v[22:25], v[146:149], v[196:199], v[22:25]
	v_mfma_f32_16x16x32_bf16 v[22:25], v[150:153], v[200:203], v[22:25]
	v_mfma_f32_16x16x32_bf16 v[18:21], v[154:157], v[196:199], v[18:21]
	v_mfma_f32_16x16x32_bf16 v[18:21], v[158:161], v[200:203], v[18:21]
	v_mfma_f32_16x16x32_bf16 v[6:9], v[146:149], v[214:217], v[6:9]
	v_mfma_f32_16x16x32_bf16 v[6:9], v[150:153], v[218:221], v[6:9]
	v_mfma_f32_16x16x32_bf16 v[2:5], v[154:157], v[214:217], v[2:5]
	v_mfma_f32_16x16x32_bf16 v[2:5], v[158:161], v[218:221], v[2:5]
	s_barrier
	s_add_i32 s73, 0, 0x18000
	s_add_i32 s74, 0, 0x1c000
	s_add_u32 s42, s42, 0x100000
	s_addc_u32 s43, s43, 0
	s_mov_b32 m0, s60
	s_nop 0
	global_load_lds_dwordx4 v178, s[42:43]
	s_mov_b32 m0, s61
	s_nop 0
	global_load_lds_dwordx4 v182, s[42:43]
	v_add_u32_e32 v142, s73, v208
	v_add_u32_e32 v158, s74, v208
	ds_read_b128 v[130:133], v142
	ds_read_b128 v[134:137], v142 offset:1024
	ds_read_b128 v[138:141], v142 offset:2048
	ds_read_b128 v[142:145], v142 offset:3072
	ds_read_b128 v[146:149], v158
	ds_read_b128 v[150:153], v158 offset:1024
	ds_read_b128 v[154:157], v158 offset:2048
	ds_read_b128 v[158:161], v158 offset:3072
	ds_read_b128 v[162:165], v211 offset:32768
	ds_read_b128 v[166:169], v211 offset:33792
	ds_read_b128 v[170:173], v211 offset:34816
	ds_read_b128 v[174:177], v211 offset:35840
	ds_read_b128 v[196:199], v211 offset:36864
	ds_read_b128 v[200:203], v211 offset:37888
	ds_read_b128 v[214:217], v211 offset:38912
	ds_read_b128 v[218:221], v211 offset:39936
	s_waitcnt vmcnt(8)
	s_waitcnt lgkmcnt(0)
	s_barrier
	s_waitcnt lgkmcnt(0)
	v_mfma_f32_16x16x32_bf16 v[126:129], v[130:133], v[162:165], v[126:129]
	v_mfma_f32_16x16x32_bf16 v[126:129], v[134:137], v[166:169], v[126:129]
	v_mfma_f32_16x16x32_bf16 v[122:125], v[138:141], v[162:165], v[122:125]
	v_mfma_f32_16x16x32_bf16 v[122:125], v[142:145], v[166:169], v[122:125]
	v_mfma_f32_16x16x32_bf16 v[110:113], v[130:133], v[170:173], v[110:113]
	v_mfma_f32_16x16x32_bf16 v[110:113], v[134:137], v[174:177], v[110:113]
	v_mfma_f32_16x16x32_bf16 v[106:109], v[138:141], v[170:173], v[106:109]
	v_mfma_f32_16x16x32_bf16 v[106:109], v[142:145], v[174:177], v[106:109]
	v_mfma_f32_16x16x32_bf16 v[94:97], v[130:133], v[196:199], v[94:97]
	v_mfma_f32_16x16x32_bf16 v[94:97], v[134:137], v[200:203], v[94:97]
	v_mfma_f32_16x16x32_bf16 v[90:93], v[138:141], v[196:199], v[90:93]
	v_mfma_f32_16x16x32_bf16 v[90:93], v[142:145], v[200:203], v[90:93]
	v_mfma_f32_16x16x32_bf16 v[78:81], v[130:133], v[214:217], v[78:81]
	v_mfma_f32_16x16x32_bf16 v[78:81], v[134:137], v[218:221], v[78:81]
	v_mfma_f32_16x16x32_bf16 v[74:77], v[138:141], v[214:217], v[74:77]
	v_mfma_f32_16x16x32_bf16 v[74:77], v[142:145], v[218:221], v[74:77]
	v_mfma_f32_16x16x32_bf16 v[118:121], v[146:149], v[162:165], v[118:121]
	v_mfma_f32_16x16x32_bf16 v[118:121], v[150:153], v[166:169], v[118:121]
	v_mfma_f32_16x16x32_bf16 v[114:117], v[154:157], v[162:165], v[114:117]
	v_mfma_f32_16x16x32_bf16 v[114:117], v[158:161], v[166:169], v[114:117]
	v_mfma_f32_16x16x32_bf16 v[102:105], v[146:149], v[170:173], v[102:105]
	v_mfma_f32_16x16x32_bf16 v[102:105], v[150:153], v[174:177], v[102:105]
	v_mfma_f32_16x16x32_bf16 v[98:101], v[154:157], v[170:173], v[98:101]
	v_mfma_f32_16x16x32_bf16 v[98:101], v[158:161], v[174:177], v[98:101]
	v_mfma_f32_16x16x32_bf16 v[86:89], v[146:149], v[196:199], v[86:89]
	v_mfma_f32_16x16x32_bf16 v[86:89], v[150:153], v[200:203], v[86:89]
	v_mfma_f32_16x16x32_bf16 v[82:85], v[154:157], v[196:199], v[82:85]
	v_mfma_f32_16x16x32_bf16 v[82:85], v[158:161], v[200:203], v[82:85]
	v_mfma_f32_16x16x32_bf16 v[70:73], v[146:149], v[214:217], v[70:73]
	v_mfma_f32_16x16x32_bf16 v[70:73], v[150:153], v[218:221], v[70:73]
	v_mfma_f32_16x16x32_bf16 v[66:69], v[154:157], v[214:217], v[66:69]
	v_mfma_f32_16x16x32_bf16 v[66:69], v[158:161], v[218:221], v[66:69]
	s_barrier
	s_add_u32 s42, s40, 0x4000
	s_addc_u32 s43, s41, 0
	s_add_i32 s73, s73, s46
	s_mov_b32 m0, s73
	s_nop 0
	global_load_lds_dwordx4 v180, s[42:43]
	s_add_i32 m0, s73, 0x2000
	s_add_u32 s40, s40, 0x104000
	s_addc_u32 s41, s41, 0
	global_load_lds_dwordx4 v184, s[42:43]
	s_add_i32 s42, s74, s46
	s_mov_b32 m0, s42
	s_nop 0
	global_load_lds_dwordx4 v180, s[40:41]
	s_add_i32 m0, s42, 0x2000
	s_nop 0
	global_load_lds_dwordx4 v184, s[40:41]
	s_mov_b32 m0, s64
	s_nop 0
	global_load_lds_dwordx4 v178, s[38:39]
	s_mov_b32 m0, s65
	s_nop 0
	global_load_lds_dwordx4 v182, s[38:39]
	ds_read_b128 v[162:165], v211 offset:49152
	ds_read_b128 v[166:169], v211 offset:50176
	ds_read_b128 v[170:173], v211 offset:51200
	ds_read_b128 v[174:177], v211 offset:52224
	ds_read_b128 v[196:199], v211 offset:53248
	ds_read_b128 v[200:203], v211 offset:54272
	ds_read_b128 v[214:217], v211 offset:55296
	ds_read_b128 v[218:221], v211 offset:56320
	s_waitcnt vmcnt(8)
	s_waitcnt lgkmcnt(0)
	s_barrier
	s_waitcnt lgkmcnt(0)
	v_mfma_f32_16x16x32_bf16 v[62:65], v[130:133], v[162:165], v[62:65]
	v_mfma_f32_16x16x32_bf16 v[62:65], v[134:137], v[166:169], v[62:65]
	v_mfma_f32_16x16x32_bf16 v[58:61], v[138:141], v[162:165], v[58:61]
	v_mfma_f32_16x16x32_bf16 v[58:61], v[142:145], v[166:169], v[58:61]
	v_mfma_f32_16x16x32_bf16 v[46:49], v[130:133], v[170:173], v[46:49]
	v_mfma_f32_16x16x32_bf16 v[46:49], v[134:137], v[174:177], v[46:49]
	v_mfma_f32_16x16x32_bf16 v[42:45], v[138:141], v[170:173], v[42:45]
	v_mfma_f32_16x16x32_bf16 v[42:45], v[142:145], v[174:177], v[42:45]
	v_mfma_f32_16x16x32_bf16 v[30:33], v[130:133], v[196:199], v[30:33]
	v_mfma_f32_16x16x32_bf16 v[30:33], v[134:137], v[200:203], v[30:33]
	v_mfma_f32_16x16x32_bf16 v[26:29], v[138:141], v[196:199], v[26:29]
	v_mfma_f32_16x16x32_bf16 v[26:29], v[142:145], v[200:203], v[26:29]
	v_mfma_f32_16x16x32_bf16 v[14:17], v[130:133], v[214:217], v[14:17]
	v_mfma_f32_16x16x32_bf16 v[14:17], v[134:137], v[218:221], v[14:17]
	v_mfma_f32_16x16x32_bf16 v[10:13], v[138:141], v[214:217], v[10:13]
	v_mfma_f32_16x16x32_bf16 v[10:13], v[142:145], v[218:221], v[10:13]
	v_mfma_f32_16x16x32_bf16 v[54:57], v[146:149], v[162:165], v[54:57]
	v_mfma_f32_16x16x32_bf16 v[54:57], v[150:153], v[166:169], v[54:57]
	v_mfma_f32_16x16x32_bf16 v[50:53], v[154:157], v[162:165], v[50:53]
	v_mfma_f32_16x16x32_bf16 v[50:53], v[158:161], v[166:169], v[50:53]
	v_mfma_f32_16x16x32_bf16 v[38:41], v[146:149], v[170:173], v[38:41]
	v_mfma_f32_16x16x32_bf16 v[38:41], v[150:153], v[174:177], v[38:41]
	v_mfma_f32_16x16x32_bf16 v[34:37], v[154:157], v[170:173], v[34:37]
	v_mfma_f32_16x16x32_bf16 v[34:37], v[158:161], v[174:177], v[34:37]
	v_mfma_f32_16x16x32_bf16 v[22:25], v[146:149], v[196:199], v[22:25]
	v_mfma_f32_16x16x32_bf16 v[22:25], v[150:153], v[200:203], v[22:25]
	v_mfma_f32_16x16x32_bf16 v[18:21], v[154:157], v[196:199], v[18:21]
	v_mfma_f32_16x16x32_bf16 v[18:21], v[158:161], v[200:203], v[18:21]
	v_mfma_f32_16x16x32_bf16 v[6:9], v[146:149], v[214:217], v[6:9]
	v_mfma_f32_16x16x32_bf16 v[6:9], v[150:153], v[218:221], v[6:9]
	v_mfma_f32_16x16x32_bf16 v[2:5], v[154:157], v[214:217], v[2:5]
	v_mfma_f32_16x16x32_bf16 v[2:5], v[158:161], v[218:221], v[2:5]
	s_barrier
	s_add_i32 s72, s72, 2
	s_add_u32 s36, s36, 0x8000
	s_addc_u32 s37, s37, 0
	s_add_u32 s70, s70, 0x8000
	s_addc_u32 s71, s71, 0
	s_cmp_gt_u32 s72, 61
	s_cbranch_scc0 .LBB0_1088
	s_and_b64 vcc, exec, s[20:21]
	s_cbranch_vccz .LBB0_1091
	s_barrier

.LBB0_1215:
	s_add_u32 s30, s28, 0xfff04000
	s_addc_u32 s31, s29, -1
	s_cmp_eq_u32 s61, 60
	s_cselect_b32 s36, s56, s30
	s_cselect_b32 s37, s21, s31
	s_cselect_b32 s34, s57, s59
	s_cselect_b32 s35, s19, s60
	s_add_u32 s30, s36, 0x4000
	s_addc_u32 s31, s37, 0
	s_add_i32 m0, s39, 0xc000
	s_nop 0
	global_load_lds_dwordx4 v140, s[28:29]
	s_add_i32 m0, s39, 0xe000
	s_nop 0
	global_load_lds_dwordx4 v142, s[28:29]
	ds_read_b128 v[160:163], v154
	ds_read_b128 v[164:167], v154 offset:1024
	ds_read_b128 v[168:171], v154 offset:2048
	ds_read_b128 v[172:175], v154 offset:3072
	ds_read_b128 v[176:179], v155
	ds_read_b128 v[180:183], v155 offset:1024
	ds_read_b128 v[184:187], v155 offset:2048
	ds_read_b128 v[188:191], v155 offset:3072
	ds_read_b128 v[192:195], v156
	ds_read_b128 v[196:199], v156 offset:1024
	ds_read_b128 v[200:203], v156 offset:2048
	ds_read_b128 v[204:207], v156 offset:3072
	ds_read_b128 v[208:211], v156 offset:4096
	ds_read_b128 v[212:215], v156 offset:5120
	ds_read_b128 v[216:219], v156 offset:6144
	ds_read_b128 v[220:223], v156 offset:7168
	s_waitcnt vmcnt(8)
	s_waitcnt lgkmcnt(0)
	s_barrier
	s_waitcnt lgkmcnt(0)
	v_mfma_f32_16x16x32_bf16 v[126:129], v[160:163], v[192:195], v[126:129]
	v_mfma_f32_16x16x32_bf16 v[126:129], v[164:167], v[196:199], v[126:129]
	v_mfma_f32_16x16x32_bf16 v[122:125], v[168:171], v[192:195], v[122:125]
	v_mfma_f32_16x16x32_bf16 v[122:125], v[172:175], v[196:199], v[122:125]
	v_mfma_f32_16x16x32_bf16 v[110:113], v[160:163], v[200:203], v[110:113]
	v_mfma_f32_16x16x32_bf16 v[110:113], v[164:167], v[204:207], v[110:113]
	v_mfma_f32_16x16x32_bf16 v[106:109], v[168:171], v[200:203], v[106:109]
	v_mfma_f32_16x16x32_bf16 v[106:109], v[172:175], v[204:207], v[106:109]
	v_mfma_f32_16x16x32_bf16 v[94:97], v[160:163], v[208:211], v[94:97]
	v_mfma_f32_16x16x32_bf16 v[94:97], v[164:167], v[212:215], v[94:97]
	v_mfma_f32_16x16x32_bf16 v[90:93], v[168:171], v[208:211], v[90:93]
	v_mfma_f32_16x16x32_bf16 v[90:93], v[172:175], v[212:215], v[90:93]
	v_mfma_f32_16x16x32_bf16 v[78:81], v[160:163], v[216:219], v[78:81]
	v_mfma_f32_16x16x32_bf16 v[78:81], v[164:167], v[220:223], v[78:81]
	v_mfma_f32_16x16x32_bf16 v[74:77], v[168:171], v[216:219], v[74:77]
	v_mfma_f32_16x16x32_bf16 v[74:77], v[172:175], v[220:223], v[74:77]
	v_mfma_f32_16x16x32_bf16 v[118:121], v[176:179], v[192:195], v[118:121]
	v_mfma_f32_16x16x32_bf16 v[118:121], v[180:183], v[196:199], v[118:121]
	v_mfma_f32_16x16x32_bf16 v[114:117], v[184:187], v[192:195], v[114:117]
	v_mfma_f32_16x16x32_bf16 v[114:117], v[188:191], v[196:199], v[114:117]
	v_mfma_f32_16x16x32_bf16 v[102:105], v[176:179], v[200:203], v[102:105]
	v_mfma_f32_16x16x32_bf16 v[102:105], v[180:183], v[204:207], v[102:105]
	v_mfma_f32_16x16x32_bf16 v[98:101], v[184:187], v[200:203], v[98:101]
	v_mfma_f32_16x16x32_bf16 v[98:101], v[188:191], v[204:207], v[98:101]
	v_mfma_f32_16x16x32_bf16 v[86:89], v[176:179], v[208:211], v[86:89]
	v_mfma_f32_16x16x32_bf16 v[86:89], v[180:183], v[212:215], v[86:89]
	v_mfma_f32_16x16x32_bf16 v[82:85], v[184:187], v[208:211], v[82:85]
	v_mfma_f32_16x16x32_bf16 v[82:85], v[188:191], v[212:215], v[82:85]
	v_mfma_f32_16x16x32_bf16 v[70:73], v[176:179], v[216:219], v[70:73]
	v_mfma_f32_16x16x32_bf16 v[70:73], v[180:183], v[220:223], v[70:73]
	v_mfma_f32_16x16x32_bf16 v[66:69], v[184:187], v[216:219], v[66:69]
	v_mfma_f32_16x16x32_bf16 v[66:69], v[188:191], v[220:223], v[66:69]
	s_barrier
	s_add_i32 s62, s47, s38
	s_mov_b32 m0, s62
	s_nop 0
	global_load_lds_dwordx4 v134, s[34:35]
	s_add_i32 m0, s62, 0x2000
	s_add_u32 s62, s34, 0x100000
	s_addc_u32 s63, s35, 0
	s_add_i32 s64, s54, s38
	global_load_lds_dwordx4 v130, s[34:35]
	s_mov_b32 m0, s64
	s_nop 0
	global_load_lds_dwordx4 v134, s[62:63]
	s_add_i32 m0, s64, 0x2000
	s_nop 0
	global_load_lds_dwordx4 v130, s[62:63]
	s_mov_b32 m0, s39
	s_nop 0
	global_load_lds_dwordx4 v136, s[36:37]
	s_mov_b32 m0, s40
	s_nop 0
	global_load_lds_dwordx4 v132, s[36:37]
	ds_read_b128 v[192:195], v156 offset:16384
	ds_read_b128 v[196:199], v156 offset:17408
	ds_read_b128 v[200:203], v156 offset:18432
	ds_read_b128 v[204:207], v156 offset:19456
	ds_read_b128 v[208:211], v156 offset:20480
	ds_read_b128 v[212:215], v156 offset:21504
	ds_read_b128 v[216:219], v156 offset:22528
	ds_read_b128 v[220:223], v156 offset:23552
	s_waitcnt vmcnt(8)
	s_waitcnt lgkmcnt(0)
	s_barrier
	s_waitcnt lgkmcnt(0)
	v_mfma_f32_16x16x32_bf16 v[62:65], v[160:163], v[192:195], v[62:65]
	v_mfma_f32_16x16x32_bf16 v[62:65], v[164:167], v[196:199], v[62:65]
	v_mfma_f32_16x16x32_bf16 v[58:61], v[168:171], v[192:195], v[58:61]
	v_mfma_f32_16x16x32_bf16 v[58:61], v[172:175], v[196:199], v[58:61]
	v_mfma_f32_16x16x32_bf16 v[46:49], v[160:163], v[200:203], v[46:49]
	v_mfma_f32_16x16x32_bf16 v[46:49], v[164:167], v[204:207], v[46:49]
	v_mfma_f32_16x16x32_bf16 v[42:45], v[168:171], v[200:203], v[42:45]
	v_mfma_f32_16x16x32_bf16 v[42:45], v[172:175], v[204:207], v[42:45]
	v_mfma_f32_16x16x32_bf16 v[30:33], v[160:163], v[208:211], v[30:33]
	v_mfma_f32_16x16x32_bf16 v[30:33], v[164:167], v[212:215], v[30:33]
	v_mfma_f32_16x16x32_bf16 v[26:29], v[168:171], v[208:211], v[26:29]
	v_mfma_f32_16x16x32_bf16 v[26:29], v[172:175], v[212:215], v[26:29]
	v_mfma_f32_16x16x32_bf16 v[14:17], v[160:163], v[216:219], v[14:17]
	v_mfma_f32_16x16x32_bf16 v[14:17], v[164:167], v[220:223], v[14:17]
	v_mfma_f32_16x16x32_bf16 v[10:13], v[168:171], v[216:219], v[10:13]
	v_mfma_f32_16x16x32_bf16 v[10:13], v[172:175], v[220:223], v[10:13]
	v_mfma_f32_16x16x32_bf16 v[54:57], v[176:179], v[192:195], v[54:57]
	v_mfma_f32_16x16x32_bf16 v[54:57], v[180:183], v[196:199], v[54:57]
	v_mfma_f32_16x16x32_bf16 v[50:53], v[184:187], v[192:195], v[50:53]
	v_mfma_f32_16x16x32_bf16 v[50:53], v[188:191], v[196:199], v[50:53]
	v_mfma_f32_16x16x32_bf16 v[38:41], v[176:179], v[200:203], v[38:41]
	v_mfma_f32_16x16x32_bf16 v[38:41], v[180:183], v[204:207], v[38:41]
	v_mfma_f32_16x16x32_bf16 v[34:37], v[184:187], v[200:203], v[34:37]
	v_mfma_f32_16x16x32_bf16 v[34:37], v[188:191], v[204:207], v[34:37]
	v_mfma_f32_16x16x32_bf16 v[22:25], v[176:179], v[208:211], v[22:25]
	v_mfma_f32_16x16x32_bf16 v[22:25], v[180:183], v[212:215], v[22:25]
	v_mfma_f32_16x16x32_bf16 v[18:21], v[184:187], v[208:211], v[18:21]
	v_mfma_f32_16x16x32_bf16 v[18:21], v[188:191], v[212:215], v[18:21]
	v_mfma_f32_16x16x32_bf16 v[6:9], v[176:179], v[216:219], v[6:9]
	v_mfma_f32_16x16x32_bf16 v[6:9], v[180:183], v[220:223], v[6:9]
	v_mfma_f32_16x16x32_bf16 v[2:5], v[184:187], v[216:219], v[2:5]
	v_mfma_f32_16x16x32_bf16 v[2:5], v[188:191], v[220:223], v[2:5]
	s_barrier
	s_add_i32 s62, 0, 0x18000
	s_add_i32 s63, 0, 0x1c000
	s_add_u32 s36, s36, 0x100000
	s_addc_u32 s37, s37, 0
	s_mov_b32 m0, s41
	s_nop 0
	global_load_lds_dwordx4 v136, s[36:37]
	s_mov_b32 m0, s42
	s_nop 0
	global_load_lds_dwordx4 v132, s[36:37]
	v_add_u32_e32 v138, s62, v153
	ds_read_b128 v[160:163], v138
	ds_read_b128 v[164:167], v138 offset:1024
	ds_read_b128 v[168:171], v138 offset:2048
	ds_read_b128 v[172:175], v138 offset:3072
	v_add_u32_e32 v138, s63, v153
	ds_read_b128 v[176:179], v138
	ds_read_b128 v[180:183], v138 offset:1024
	ds_read_b128 v[184:187], v138 offset:2048
	ds_read_b128 v[188:191], v138 offset:3072
	ds_read_b128 v[192:195], v156 offset:32768
	ds_read_b128 v[196:199], v156 offset:33792
	ds_read_b128 v[200:203], v156 offset:34816
	ds_read_b128 v[204:207], v156 offset:35840
	ds_read_b128 v[208:211], v156 offset:36864
	ds_read_b128 v[212:215], v156 offset:37888
	ds_read_b128 v[216:219], v156 offset:38912
	ds_read_b128 v[220:223], v156 offset:39936
	s_waitcnt vmcnt(8)
	s_waitcnt lgkmcnt(0)
	s_barrier
	s_waitcnt lgkmcnt(0)
	v_mfma_f32_16x16x32_bf16 v[126:129], v[160:163], v[192:195], v[126:129]
	v_mfma_f32_16x16x32_bf16 v[126:129], v[164:167], v[196:199], v[126:129]
	v_mfma_f32_16x16x32_bf16 v[122:125], v[168:171], v[192:195], v[122:125]
	v_mfma_f32_16x16x32_bf16 v[122:125], v[172:175], v[196:199], v[122:125]
	v_mfma_f32_16x16x32_bf16 v[110:113], v[160:163], v[200:203], v[110:113]
	v_mfma_f32_16x16x32_bf16 v[110:113], v[164:167], v[204:207], v[110:113]
	v_mfma_f32_16x16x32_bf16 v[106:109], v[168:171], v[200:203], v[106:109]
	v_mfma_f32_16x16x32_bf16 v[106:109], v[172:175], v[204:207], v[106:109]
	v_mfma_f32_16x16x32_bf16 v[94:97], v[160:163], v[208:211], v[94:97]
	v_mfma_f32_16x16x32_bf16 v[94:97], v[164:167], v[212:215], v[94:97]
	v_mfma_f32_16x16x32_bf16 v[90:93], v[168:171], v[208:211], v[90:93]
	v_mfma_f32_16x16x32_bf16 v[90:93], v[172:175], v[212:215], v[90:93]
	v_mfma_f32_16x16x32_bf16 v[78:81], v[160:163], v[216:219], v[78:81]
	v_mfma_f32_16x16x32_bf16 v[78:81], v[164:167], v[220:223], v[78:81]
	v_mfma_f32_16x16x32_bf16 v[74:77], v[168:171], v[216:219], v[74:77]
	v_mfma_f32_16x16x32_bf16 v[74:77], v[172:175], v[220:223], v[74:77]
	v_mfma_f32_16x16x32_bf16 v[118:121], v[176:179], v[192:195], v[118:121]
	v_mfma_f32_16x16x32_bf16 v[118:121], v[180:183], v[196:199], v[118:121]
	v_mfma_f32_16x16x32_bf16 v[114:117], v[184:187], v[192:195], v[114:117]
	v_mfma_f32_16x16x32_bf16 v[114:117], v[188:191], v[196:199], v[114:117]
	v_mfma_f32_16x16x32_bf16 v[102:105], v[176:179], v[200:203], v[102:105]
	v_mfma_f32_16x16x32_bf16 v[102:105], v[180:183], v[204:207], v[102:105]
	v_mfma_f32_16x16x32_bf16 v[98:101], v[184:187], v[200:203], v[98:101]
	v_mfma_f32_16x16x32_bf16 v[98:101], v[188:191], v[204:207], v[98:101]
	v_mfma_f32_16x16x32_bf16 v[86:89], v[176:179], v[208:211], v[86:89]
	v_mfma_f32_16x16x32_bf16 v[86:89], v[180:183], v[212:215], v[86:89]
	v_mfma_f32_16x16x32_bf16 v[82:85], v[184:187], v[208:211], v[82:85]
	v_mfma_f32_16x16x32_bf16 v[82:85], v[188:191], v[212:215], v[82:85]
	v_mfma_f32_16x16x32_bf16 v[70:73], v[176:179], v[216:219], v[70:73]
	v_mfma_f32_16x16x32_bf16 v[70:73], v[180:183], v[220:223], v[70:73]
	v_mfma_f32_16x16x32_bf16 v[66:69], v[184:187], v[216:219], v[66:69]
	v_mfma_f32_16x16x32_bf16 v[66:69], v[188:191], v[220:223], v[66:69]
	s_barrier
	s_add_u32 s36, s34, 0x4000
	s_addc_u32 s37, s35, 0
	s_add_i32 s62, s62, s38
	s_mov_b32 m0, s62
	s_nop 0
	global_load_lds_dwordx4 v134, s[36:37]
	s_add_i32 m0, s62, 0x2000
	s_add_u32 s34, s34, 0x104000
	s_addc_u32 s35, s35, 0
	global_load_lds_dwordx4 v130, s[36:37]
	s_add_i32 s36, s63, s38
	s_mov_b32 m0, s36
	s_nop 0
	global_load_lds_dwordx4 v134, s[34:35]
	s_add_i32 m0, s36, 0x2000
	s_nop 0
	global_load_lds_dwordx4 v130, s[34:35]
	s_mov_b32 m0, s45
	s_nop 0
	global_load_lds_dwordx4 v136, s[30:31]
	s_mov_b32 m0, s46
	s_nop 0
	global_load_lds_dwordx4 v132, s[30:31]
	ds_read_b128 v[192:195], v156 offset:49152
	ds_read_b128 v[196:199], v156 offset:50176
	ds_read_b128 v[200:203], v156 offset:51200
	ds_read_b128 v[204:207], v156 offset:52224
	ds_read_b128 v[208:211], v156 offset:53248
	ds_read_b128 v[212:215], v156 offset:54272
	ds_read_b128 v[216:219], v156 offset:55296
	ds_read_b128 v[220:223], v156 offset:56320
	s_waitcnt vmcnt(8)
	s_waitcnt lgkmcnt(0)
	s_barrier
	s_waitcnt lgkmcnt(0)
	v_mfma_f32_16x16x32_bf16 v[62:65], v[160:163], v[192:195], v[62:65]
	v_mfma_f32_16x16x32_bf16 v[62:65], v[164:167], v[196:199], v[62:65]
	v_mfma_f32_16x16x32_bf16 v[58:61], v[168:171], v[192:195], v[58:61]
	v_mfma_f32_16x16x32_bf16 v[58:61], v[172:175], v[196:199], v[58:61]
	v_mfma_f32_16x16x32_bf16 v[46:49], v[160:163], v[200:203], v[46:49]
	v_mfma_f32_16x16x32_bf16 v[46:49], v[164:167], v[204:207], v[46:49]
	v_mfma_f32_16x16x32_bf16 v[42:45], v[168:171], v[200:203], v[42:45]
	v_mfma_f32_16x16x32_bf16 v[42:45], v[172:175], v[204:207], v[42:45]
	v_mfma_f32_16x16x32_bf16 v[30:33], v[160:163], v[208:211], v[30:33]
	v_mfma_f32_16x16x32_bf16 v[30:33], v[164:167], v[212:215], v[30:33]
	v_mfma_f32_16x16x32_bf16 v[26:29], v[168:171], v[208:211], v[26:29]
	v_mfma_f32_16x16x32_bf16 v[26:29], v[172:175], v[212:215], v[26:29]
	v_mfma_f32_16x16x32_bf16 v[14:17], v[160:163], v[216:219], v[14:17]
	v_mfma_f32_16x16x32_bf16 v[14:17], v[164:167], v[220:223], v[14:17]
	v_mfma_f32_16x16x32_bf16 v[10:13], v[168:171], v[216:219], v[10:13]
	v_mfma_f32_16x16x32_bf16 v[10:13], v[172:175], v[220:223], v[10:13]
	v_mfma_f32_16x16x32_bf16 v[54:57], v[176:179], v[192:195], v[54:57]
	v_mfma_f32_16x16x32_bf16 v[54:57], v[180:183], v[196:199], v[54:57]
	v_mfma_f32_16x16x32_bf16 v[50:53], v[184:187], v[192:195], v[50:53]
	v_mfma_f32_16x16x32_bf16 v[50:53], v[188:191], v[196:199], v[50:53]
	v_mfma_f32_16x16x32_bf16 v[38:41], v[176:179], v[200:203], v[38:41]
	v_mfma_f32_16x16x32_bf16 v[38:41], v[180:183], v[204:207], v[38:41]
	v_mfma_f32_16x16x32_bf16 v[34:37], v[184:187], v[200:203], v[34:37]
	v_mfma_f32_16x16x32_bf16 v[34:37], v[188:191], v[204:207], v[34:37]
	v_mfma_f32_16x16x32_bf16 v[22:25], v[176:179], v[208:211], v[22:25]
	v_mfma_f32_16x16x32_bf16 v[22:25], v[180:183], v[212:215], v[22:25]
	v_mfma_f32_16x16x32_bf16 v[18:21], v[184:187], v[208:211], v[18:21]
	v_mfma_f32_16x16x32_bf16 v[18:21], v[188:191], v[212:215], v[18:21]
	v_mfma_f32_16x16x32_bf16 v[6:9], v[176:179], v[216:219], v[6:9]
	v_mfma_f32_16x16x32_bf16 v[6:9], v[180:183], v[220:223], v[6:9]
	v_mfma_f32_16x16x32_bf16 v[2:5], v[184:187], v[216:219], v[2:5]
	v_mfma_f32_16x16x32_bf16 v[2:5], v[188:191], v[220:223], v[2:5]
	s_barrier
	s_add_i32 s61, s61, 2
	s_add_u32 s28, s28, 0x8000
	s_addc_u32 s29, s29, 0
	s_add_u32 s59, s59, 0x8000
	s_addc_u32 s60, s60, 0
	s_cmp_gt_u32 s61, 61
	s_cbranch_scc0 .LBB0_1215
	s_and_b64 vcc, exec, s[16:17]
	s_cbranch_vccz .LBB0_1218
	s_barrier

.LBB0_1292:
	s_add_u32 s42, s40, 0xffc04000
	s_addc_u32 s43, s41, -1
	s_cmpk_eq_i32 s66, 0xfc
	s_cselect_b32 s46, s29, s42
	s_cselect_b32 s47, s14, s43
	s_cselect_b32 s44, s37, s39
	s_cselect_b32 s45, s27, s65
	s_add_u32 s42, s46, 0x4000
	s_addc_u32 s43, s47, 0
	s_add_i32 m0, s53, 0xc000
	s_nop 0
	global_load_lds_dwordx4 v166, s[40:41]
	s_add_i32 m0, s53, 0xe000
	s_nop 0
	global_load_lds_dwordx4 v168, s[40:41]
	ds_read_b128 v[130:133], v206
	ds_read_b128 v[134:137], v206 offset:1024
	ds_read_b128 v[138:141], v206 offset:2048
	ds_read_b128 v[142:145], v206 offset:3072
	ds_read_b128 v[146:149], v207
	ds_read_b128 v[150:153], v207 offset:1024
	ds_read_b128 v[176:179], v207 offset:2048
	ds_read_b128 v[180:183], v207 offset:3072
	ds_read_b128 v[184:187], v208
	ds_read_b128 v[188:191], v208 offset:1024
	ds_read_b128 v[192:195], v208 offset:2048
	ds_read_b128 v[196:199], v208 offset:3072
	ds_read_b128 v[210:213], v208 offset:4096
	ds_read_b128 v[214:217], v208 offset:5120
	ds_read_b128 v[218:221], v208 offset:6144
	ds_read_b128 v[222:225], v208 offset:7168
	s_waitcnt vmcnt(8)
	s_waitcnt lgkmcnt(0)
	s_barrier
	s_waitcnt lgkmcnt(0)
	v_mfma_f32_16x16x32_bf16 v[126:129], v[130:133], v[184:187], v[126:129]
	v_mfma_f32_16x16x32_bf16 v[126:129], v[134:137], v[188:191], v[126:129]
	v_mfma_f32_16x16x32_bf16 v[122:125], v[138:141], v[184:187], v[122:125]
	v_mfma_f32_16x16x32_bf16 v[122:125], v[142:145], v[188:191], v[122:125]
	v_mfma_f32_16x16x32_bf16 v[110:113], v[130:133], v[192:195], v[110:113]
	v_mfma_f32_16x16x32_bf16 v[110:113], v[134:137], v[196:199], v[110:113]
	v_mfma_f32_16x16x32_bf16 v[106:109], v[138:141], v[192:195], v[106:109]
	v_mfma_f32_16x16x32_bf16 v[106:109], v[142:145], v[196:199], v[106:109]
	v_mfma_f32_16x16x32_bf16 v[94:97], v[130:133], v[210:213], v[94:97]
	v_mfma_f32_16x16x32_bf16 v[94:97], v[134:137], v[214:217], v[94:97]
	v_mfma_f32_16x16x32_bf16 v[90:93], v[138:141], v[210:213], v[90:93]
	v_mfma_f32_16x16x32_bf16 v[90:93], v[142:145], v[214:217], v[90:93]
	v_mfma_f32_16x16x32_bf16 v[78:81], v[130:133], v[218:221], v[78:81]
	v_mfma_f32_16x16x32_bf16 v[78:81], v[134:137], v[222:225], v[78:81]
	v_mfma_f32_16x16x32_bf16 v[74:77], v[138:141], v[218:221], v[74:77]
	v_mfma_f32_16x16x32_bf16 v[74:77], v[142:145], v[222:225], v[74:77]
	v_mfma_f32_16x16x32_bf16 v[118:121], v[146:149], v[184:187], v[118:121]
	v_mfma_f32_16x16x32_bf16 v[118:121], v[150:153], v[188:191], v[118:121]
	v_mfma_f32_16x16x32_bf16 v[114:117], v[176:179], v[184:187], v[114:117]
	v_mfma_f32_16x16x32_bf16 v[114:117], v[180:183], v[188:191], v[114:117]
	v_mfma_f32_16x16x32_bf16 v[102:105], v[146:149], v[192:195], v[102:105]
	v_mfma_f32_16x16x32_bf16 v[102:105], v[150:153], v[196:199], v[102:105]
	v_mfma_f32_16x16x32_bf16 v[98:101], v[176:179], v[192:195], v[98:101]
	v_mfma_f32_16x16x32_bf16 v[98:101], v[180:183], v[196:199], v[98:101]
	v_mfma_f32_16x16x32_bf16 v[86:89], v[146:149], v[210:213], v[86:89]
	v_mfma_f32_16x16x32_bf16 v[86:89], v[150:153], v[214:217], v[86:89]
	v_mfma_f32_16x16x32_bf16 v[82:85], v[176:179], v[210:213], v[82:85]
	v_mfma_f32_16x16x32_bf16 v[82:85], v[180:183], v[214:217], v[82:85]
	v_mfma_f32_16x16x32_bf16 v[70:73], v[146:149], v[218:221], v[70:73]
	v_mfma_f32_16x16x32_bf16 v[70:73], v[150:153], v[222:225], v[70:73]
	v_mfma_f32_16x16x32_bf16 v[66:69], v[176:179], v[218:221], v[66:69]
	v_mfma_f32_16x16x32_bf16 v[66:69], v[180:183], v[222:225], v[66:69]
	s_barrier
	s_add_i32 s67, s62, s52
	s_mov_b32 m0, s67
	s_nop 0
	global_load_lds_dwordx4 v156, s[44:45]
	s_add_i32 m0, s67, 0x2000
	s_add_u32 s68, s44, 0x400000
	s_addc_u32 s69, s45, 0
	s_add_i32 s67, s63, s52
	global_load_lds_dwordx4 v160, s[44:45]
	s_mov_b32 m0, s67
	s_nop 0
	global_load_lds_dwordx4 v156, s[68:69]
	s_add_i32 m0, s67, 0x2000
	s_nop 0
	global_load_lds_dwordx4 v160, s[68:69]
	s_mov_b32 m0, s53
	s_nop 0
	global_load_lds_dwordx4 v154, s[46:47]
	s_mov_b32 m0, s54
	s_nop 0
	global_load_lds_dwordx4 v158, s[46:47]
	ds_read_b128 v[184:187], v208 offset:16384
	ds_read_b128 v[188:191], v208 offset:17408
	ds_read_b128 v[192:195], v208 offset:18432
	ds_read_b128 v[196:199], v208 offset:19456
	ds_read_b128 v[210:213], v208 offset:20480
	ds_read_b128 v[214:217], v208 offset:21504
	ds_read_b128 v[218:221], v208 offset:22528
	ds_read_b128 v[222:225], v208 offset:23552
	s_waitcnt vmcnt(8)
	s_waitcnt lgkmcnt(0)
	s_barrier
	s_waitcnt lgkmcnt(0)
	v_mfma_f32_16x16x32_bf16 v[62:65], v[130:133], v[184:187], v[62:65]
	v_mfma_f32_16x16x32_bf16 v[62:65], v[134:137], v[188:191], v[62:65]
	v_mfma_f32_16x16x32_bf16 v[58:61], v[138:141], v[184:187], v[58:61]
	v_mfma_f32_16x16x32_bf16 v[58:61], v[142:145], v[188:191], v[58:61]
	v_mfma_f32_16x16x32_bf16 v[46:49], v[130:133], v[192:195], v[46:49]
	v_mfma_f32_16x16x32_bf16 v[46:49], v[134:137], v[196:199], v[46:49]
	v_mfma_f32_16x16x32_bf16 v[42:45], v[138:141], v[192:195], v[42:45]
	v_mfma_f32_16x16x32_bf16 v[42:45], v[142:145], v[196:199], v[42:45]
	v_mfma_f32_16x16x32_bf16 v[30:33], v[130:133], v[210:213], v[30:33]
	v_mfma_f32_16x16x32_bf16 v[30:33], v[134:137], v[214:217], v[30:33]
	v_mfma_f32_16x16x32_bf16 v[26:29], v[138:141], v[210:213], v[26:29]
	v_mfma_f32_16x16x32_bf16 v[26:29], v[142:145], v[214:217], v[26:29]
	v_mfma_f32_16x16x32_bf16 v[14:17], v[130:133], v[218:221], v[14:17]
	v_mfma_f32_16x16x32_bf16 v[14:17], v[134:137], v[222:225], v[14:17]
	v_mfma_f32_16x16x32_bf16 v[10:13], v[138:141], v[218:221], v[10:13]
	v_mfma_f32_16x16x32_bf16 v[10:13], v[142:145], v[222:225], v[10:13]
	v_mfma_f32_16x16x32_bf16 v[54:57], v[146:149], v[184:187], v[54:57]
	v_mfma_f32_16x16x32_bf16 v[54:57], v[150:153], v[188:191], v[54:57]
	v_mfma_f32_16x16x32_bf16 v[50:53], v[176:179], v[184:187], v[50:53]
	v_mfma_f32_16x16x32_bf16 v[50:53], v[180:183], v[188:191], v[50:53]
	v_mfma_f32_16x16x32_bf16 v[38:41], v[146:149], v[192:195], v[38:41]
	v_mfma_f32_16x16x32_bf16 v[38:41], v[150:153], v[196:199], v[38:41]
	v_mfma_f32_16x16x32_bf16 v[34:37], v[176:179], v[192:195], v[34:37]
	v_mfma_f32_16x16x32_bf16 v[34:37], v[180:183], v[196:199], v[34:37]
	v_mfma_f32_16x16x32_bf16 v[22:25], v[146:149], v[210:213], v[22:25]
	v_mfma_f32_16x16x32_bf16 v[22:25], v[150:153], v[214:217], v[22:25]
	v_mfma_f32_16x16x32_bf16 v[18:21], v[176:179], v[210:213], v[18:21]
	v_mfma_f32_16x16x32_bf16 v[18:21], v[180:183], v[214:217], v[18:21]
	v_mfma_f32_16x16x32_bf16 v[6:9], v[146:149], v[218:221], v[6:9]
	v_mfma_f32_16x16x32_bf16 v[6:9], v[150:153], v[222:225], v[6:9]
	v_mfma_f32_16x16x32_bf16 v[2:5], v[176:179], v[218:221], v[2:5]
	v_mfma_f32_16x16x32_bf16 v[2:5], v[180:183], v[222:225], v[2:5]
	s_barrier
	s_add_i32 s67, 0, 0x18000
	s_add_i32 s68, 0, 0x1c000
	s_add_u32 s46, s46, 0x400000
	s_addc_u32 s47, s47, 0
	s_mov_b32 m0, s55
	s_nop 0
	global_load_lds_dwordx4 v154, s[46:47]
	s_mov_b32 m0, s56
	s_nop 0
	global_load_lds_dwordx4 v158, s[46:47]
	v_add_u32_e32 v142, s67, v203
	v_add_u32_e32 v162, s68, v203
	ds_read_b128 v[130:133], v142
	ds_read_b128 v[134:137], v142 offset:1024
	ds_read_b128 v[138:141], v142 offset:2048
	ds_read_b128 v[142:145], v142 offset:3072
	ds_read_b128 v[146:149], v162
	ds_read_b128 v[150:153], v162 offset:1024
	ds_read_b128 v[176:179], v162 offset:2048
	ds_read_b128 v[180:183], v162 offset:3072
	ds_read_b128 v[184:187], v208 offset:32768
	ds_read_b128 v[188:191], v208 offset:33792
	ds_read_b128 v[192:195], v208 offset:34816
	ds_read_b128 v[196:199], v208 offset:35840
	ds_read_b128 v[210:213], v208 offset:36864
	ds_read_b128 v[214:217], v208 offset:37888
	ds_read_b128 v[218:221], v208 offset:38912
	ds_read_b128 v[222:225], v208 offset:39936
	s_waitcnt vmcnt(8)
	s_waitcnt lgkmcnt(0)
	s_barrier
	s_waitcnt lgkmcnt(0)
	v_mfma_f32_16x16x32_bf16 v[126:129], v[130:133], v[184:187], v[126:129]
	v_mfma_f32_16x16x32_bf16 v[126:129], v[134:137], v[188:191], v[126:129]
	v_mfma_f32_16x16x32_bf16 v[122:125], v[138:141], v[184:187], v[122:125]
	v_mfma_f32_16x16x32_bf16 v[122:125], v[142:145], v[188:191], v[122:125]
	v_mfma_f32_16x16x32_bf16 v[110:113], v[130:133], v[192:195], v[110:113]
	v_mfma_f32_16x16x32_bf16 v[110:113], v[134:137], v[196:199], v[110:113]
	v_mfma_f32_16x16x32_bf16 v[106:109], v[138:141], v[192:195], v[106:109]
	v_mfma_f32_16x16x32_bf16 v[106:109], v[142:145], v[196:199], v[106:109]
	v_mfma_f32_16x16x32_bf16 v[94:97], v[130:133], v[210:213], v[94:97]
	v_mfma_f32_16x16x32_bf16 v[94:97], v[134:137], v[214:217], v[94:97]
	v_mfma_f32_16x16x32_bf16 v[90:93], v[138:141], v[210:213], v[90:93]
	v_mfma_f32_16x16x32_bf16 v[90:93], v[142:145], v[214:217], v[90:93]
	v_mfma_f32_16x16x32_bf16 v[78:81], v[130:133], v[218:221], v[78:81]
	v_mfma_f32_16x16x32_bf16 v[78:81], v[134:137], v[222:225], v[78:81]
	v_mfma_f32_16x16x32_bf16 v[74:77], v[138:141], v[218:221], v[74:77]
	v_mfma_f32_16x16x32_bf16 v[74:77], v[142:145], v[222:225], v[74:77]
	v_mfma_f32_16x16x32_bf16 v[118:121], v[146:149], v[184:187], v[118:121]
	v_mfma_f32_16x16x32_bf16 v[118:121], v[150:153], v[188:191], v[118:121]
	v_mfma_f32_16x16x32_bf16 v[114:117], v[176:179], v[184:187], v[114:117]
	v_mfma_f32_16x16x32_bf16 v[114:117], v[180:183], v[188:191], v[114:117]
	v_mfma_f32_16x16x32_bf16 v[102:105], v[146:149], v[192:195], v[102:105]
	v_mfma_f32_16x16x32_bf16 v[102:105], v[150:153], v[196:199], v[102:105]
	v_mfma_f32_16x16x32_bf16 v[98:101], v[176:179], v[192:195], v[98:101]
	v_mfma_f32_16x16x32_bf16 v[98:101], v[180:183], v[196:199], v[98:101]
	v_mfma_f32_16x16x32_bf16 v[86:89], v[146:149], v[210:213], v[86:89]
	v_mfma_f32_16x16x32_bf16 v[86:89], v[150:153], v[214:217], v[86:89]
	v_mfma_f32_16x16x32_bf16 v[82:85], v[176:179], v[210:213], v[82:85]
	v_mfma_f32_16x16x32_bf16 v[82:85], v[180:183], v[214:217], v[82:85]
	v_mfma_f32_16x16x32_bf16 v[70:73], v[146:149], v[218:221], v[70:73]
	v_mfma_f32_16x16x32_bf16 v[70:73], v[150:153], v[222:225], v[70:73]
	v_mfma_f32_16x16x32_bf16 v[66:69], v[176:179], v[218:221], v[66:69]
	v_mfma_f32_16x16x32_bf16 v[66:69], v[180:183], v[222:225], v[66:69]
	s_barrier
	s_add_u32 s46, s44, 0x4000
	s_addc_u32 s47, s45, 0
	s_add_i32 s67, s67, s52
	s_mov_b32 m0, s67
	s_nop 0
	global_load_lds_dwordx4 v156, s[46:47]
	s_add_i32 m0, s67, 0x2000
	s_add_u32 s44, s44, 0x404000
	s_addc_u32 s45, s45, 0
	global_load_lds_dwordx4 v160, s[46:47]
	s_add_i32 s46, s68, s52
	s_mov_b32 m0, s46
	s_nop 0
	global_load_lds_dwordx4 v156, s[44:45]
	s_add_i32 m0, s46, 0x2000
	s_nop 0
	global_load_lds_dwordx4 v160, s[44:45]
	s_mov_b32 m0, s60
	s_nop 0
	global_load_lds_dwordx4 v154, s[42:43]
	s_mov_b32 m0, s61
	s_nop 0
	global_load_lds_dwordx4 v158, s[42:43]
	ds_read_b128 v[184:187], v208 offset:49152
	ds_read_b128 v[188:191], v208 offset:50176
	ds_read_b128 v[192:195], v208 offset:51200
	ds_read_b128 v[196:199], v208 offset:52224
	ds_read_b128 v[210:213], v208 offset:53248
	ds_read_b128 v[214:217], v208 offset:54272
	ds_read_b128 v[218:221], v208 offset:55296
	ds_read_b128 v[222:225], v208 offset:56320
	s_waitcnt vmcnt(8)
	s_waitcnt lgkmcnt(0)
	s_barrier
	s_waitcnt lgkmcnt(0)
	v_mfma_f32_16x16x32_bf16 v[62:65], v[130:133], v[184:187], v[62:65]
	v_mfma_f32_16x16x32_bf16 v[62:65], v[134:137], v[188:191], v[62:65]
	v_mfma_f32_16x16x32_bf16 v[58:61], v[138:141], v[184:187], v[58:61]
	v_mfma_f32_16x16x32_bf16 v[58:61], v[142:145], v[188:191], v[58:61]
	v_mfma_f32_16x16x32_bf16 v[46:49], v[130:133], v[192:195], v[46:49]
	v_mfma_f32_16x16x32_bf16 v[46:49], v[134:137], v[196:199], v[46:49]
	v_mfma_f32_16x16x32_bf16 v[42:45], v[138:141], v[192:195], v[42:45]
	v_mfma_f32_16x16x32_bf16 v[42:45], v[142:145], v[196:199], v[42:45]
	v_mfma_f32_16x16x32_bf16 v[30:33], v[130:133], v[210:213], v[30:33]
	v_mfma_f32_16x16x32_bf16 v[30:33], v[134:137], v[214:217], v[30:33]
	v_mfma_f32_16x16x32_bf16 v[26:29], v[138:141], v[210:213], v[26:29]
	v_mfma_f32_16x16x32_bf16 v[26:29], v[142:145], v[214:217], v[26:29]
	v_mfma_f32_16x16x32_bf16 v[14:17], v[130:133], v[218:221], v[14:17]
	v_mfma_f32_16x16x32_bf16 v[14:17], v[134:137], v[222:225], v[14:17]
	v_mfma_f32_16x16x32_bf16 v[10:13], v[138:141], v[218:221], v[10:13]
	v_mfma_f32_16x16x32_bf16 v[10:13], v[142:145], v[222:225], v[10:13]
	v_mfma_f32_16x16x32_bf16 v[54:57], v[146:149], v[184:187], v[54:57]
	v_mfma_f32_16x16x32_bf16 v[54:57], v[150:153], v[188:191], v[54:57]
	v_mfma_f32_16x16x32_bf16 v[50:53], v[176:179], v[184:187], v[50:53]
	v_mfma_f32_16x16x32_bf16 v[50:53], v[180:183], v[188:191], v[50:53]
	v_mfma_f32_16x16x32_bf16 v[38:41], v[146:149], v[192:195], v[38:41]
	v_mfma_f32_16x16x32_bf16 v[38:41], v[150:153], v[196:199], v[38:41]
	v_mfma_f32_16x16x32_bf16 v[34:37], v[176:179], v[192:195], v[34:37]
	v_mfma_f32_16x16x32_bf16 v[34:37], v[180:183], v[196:199], v[34:37]
	v_mfma_f32_16x16x32_bf16 v[22:25], v[146:149], v[210:213], v[22:25]
	v_mfma_f32_16x16x32_bf16 v[22:25], v[150:153], v[214:217], v[22:25]
	v_mfma_f32_16x16x32_bf16 v[18:21], v[176:179], v[210:213], v[18:21]
	v_mfma_f32_16x16x32_bf16 v[18:21], v[180:183], v[214:217], v[18:21]
	v_mfma_f32_16x16x32_bf16 v[6:9], v[146:149], v[218:221], v[6:9]
	v_mfma_f32_16x16x32_bf16 v[6:9], v[150:153], v[222:225], v[6:9]
	v_mfma_f32_16x16x32_bf16 v[2:5], v[176:179], v[218:221], v[2:5]
	v_mfma_f32_16x16x32_bf16 v[2:5], v[180:183], v[222:225], v[2:5]
	s_barrier
	s_add_i32 s66, s66, 2
	s_add_u32 s40, s40, 0x8000
	s_addc_u32 s41, s41, 0
	s_add_u32 s39, s39, 0x8000
	s_addc_u32 s65, s65, 0
	s_cmpk_gt_u32 s66, 0xfd
	s_cbranch_scc0 .LBB0_1292
	s_and_b64 vcc, exec, s[24:25]
	s_cbranch_vccz .LBB0_1295
	s_barrier

.LBB0_1387:
	s_add_u32 s34, s30, 0xfff04000
	s_addc_u32 s35, s31, -1
	s_cmp_eq_u32 s54, 60
	s_cselect_b32 s38, s27, s34
	s_cselect_b32 s39, s21, s35
	s_cselect_b32 s36, s29, s52
	s_cselect_b32 s37, s19, s53
	s_add_u32 s34, s38, 0x4000
	s_addc_u32 s35, s39, 0
	s_add_i32 m0, s40, 0xc000
	s_nop 0
	global_load_lds_dwordx4 v172, s[30:31]
	s_add_i32 m0, s40, 0xe000
	s_nop 0
	global_load_lds_dwordx4 v174, s[30:31]
	ds_read_b128 v[62:65], v189
	ds_read_b128 v[66:69], v189 offset:1024
	ds_read_b128 v[74:77], v189 offset:2048
	ds_read_b128 v[78:81], v189 offset:3072
	ds_read_b128 v[146:149], v195
	ds_read_b128 v[150:153], v195 offset:1024
	ds_read_b128 v[154:157], v195 offset:2048
	ds_read_b128 v[158:161], v195 offset:3072
	ds_read_b128 v[190:193], v197
	ds_read_b128 v[198:201], v197 offset:1024
	ds_read_b128 v[202:205], v197 offset:2048
	ds_read_b128 v[206:209], v197 offset:3072
	ds_read_b128 v[210:213], v197 offset:4096
	ds_read_b128 v[214:217], v197 offset:5120
	ds_read_b128 v[218:221], v197 offset:6144
	ds_read_b128 v[222:225], v197 offset:7168
	s_waitcnt vmcnt(8)
	s_waitcnt lgkmcnt(0)
	s_barrier
	s_waitcnt lgkmcnt(0)
	v_mfma_f32_16x16x32_bf16 v[142:145], v[62:65], v[190:193], v[142:145]
	v_mfma_f32_16x16x32_bf16 v[142:145], v[66:69], v[198:201], v[142:145]
	v_mfma_f32_16x16x32_bf16 v[138:141], v[74:77], v[190:193], v[138:141]
	v_mfma_f32_16x16x32_bf16 v[138:141], v[78:81], v[198:201], v[138:141]
	v_mfma_f32_16x16x32_bf16 v[126:129], v[62:65], v[202:205], v[126:129]
	v_mfma_f32_16x16x32_bf16 v[126:129], v[66:69], v[206:209], v[126:129]
	v_mfma_f32_16x16x32_bf16 v[122:125], v[74:77], v[202:205], v[122:125]
	v_mfma_f32_16x16x32_bf16 v[122:125], v[78:81], v[206:209], v[122:125]
	v_mfma_f32_16x16x32_bf16 v[110:113], v[62:65], v[210:213], v[110:113]
	v_mfma_f32_16x16x32_bf16 v[110:113], v[66:69], v[214:217], v[110:113]
	v_mfma_f32_16x16x32_bf16 v[106:109], v[74:77], v[210:213], v[106:109]
	v_mfma_f32_16x16x32_bf16 v[106:109], v[78:81], v[214:217], v[106:109]
	v_mfma_f32_16x16x32_bf16 v[94:97], v[62:65], v[218:221], v[94:97]
	v_mfma_f32_16x16x32_bf16 v[94:97], v[66:69], v[222:225], v[94:97]
	v_mfma_f32_16x16x32_bf16 v[90:93], v[74:77], v[218:221], v[90:93]
	v_mfma_f32_16x16x32_bf16 v[90:93], v[78:81], v[222:225], v[90:93]
	v_mfma_f32_16x16x32_bf16 v[134:137], v[146:149], v[190:193], v[134:137]
	v_mfma_f32_16x16x32_bf16 v[134:137], v[150:153], v[198:201], v[134:137]
	v_mfma_f32_16x16x32_bf16 v[130:133], v[154:157], v[190:193], v[130:133]
	v_mfma_f32_16x16x32_bf16 v[130:133], v[158:161], v[198:201], v[130:133]
	v_mfma_f32_16x16x32_bf16 v[118:121], v[146:149], v[202:205], v[118:121]
	v_mfma_f32_16x16x32_bf16 v[118:121], v[150:153], v[206:209], v[118:121]
	v_mfma_f32_16x16x32_bf16 v[114:117], v[154:157], v[202:205], v[114:117]
	v_mfma_f32_16x16x32_bf16 v[114:117], v[158:161], v[206:209], v[114:117]
	v_mfma_f32_16x16x32_bf16 v[102:105], v[146:149], v[210:213], v[102:105]
	v_mfma_f32_16x16x32_bf16 v[102:105], v[150:153], v[214:217], v[102:105]
	v_mfma_f32_16x16x32_bf16 v[98:101], v[154:157], v[210:213], v[98:101]
	v_mfma_f32_16x16x32_bf16 v[98:101], v[158:161], v[214:217], v[98:101]
	v_mfma_f32_16x16x32_bf16 v[86:89], v[146:149], v[218:221], v[86:89]
	v_mfma_f32_16x16x32_bf16 v[86:89], v[150:153], v[222:225], v[86:89]
	v_mfma_f32_16x16x32_bf16 v[82:85], v[154:157], v[218:221], v[82:85]
	v_mfma_f32_16x16x32_bf16 v[82:85], v[158:161], v[222:225], v[82:85]
	s_barrier
	s_add_i32 s55, s50, s33
	s_mov_b32 m0, s55
	s_nop 0
	global_load_lds_dwordx4 v166, s[36:37]
	s_add_i32 m0, s55, 0x2000
	s_add_u32 s56, s36, 0x100000
	s_addc_u32 s57, s37, 0
	s_add_i32 s55, s51, s33
	global_load_lds_dwordx4 v162, s[36:37]
	s_mov_b32 m0, s55
	s_nop 0
	global_load_lds_dwordx4 v166, s[56:57]
	s_add_i32 m0, s55, 0x2000
	s_nop 0
	global_load_lds_dwordx4 v162, s[56:57]
	s_mov_b32 m0, s40
	s_nop 0
	global_load_lds_dwordx4 v168, s[38:39]
	s_mov_b32 m0, s41
	s_nop 0
	global_load_lds_dwordx4 v164, s[38:39]
	ds_read_b128 v[190:193], v197 offset:16384
	ds_read_b128 v[198:201], v197 offset:17408
	ds_read_b128 v[202:205], v197 offset:18432
	ds_read_b128 v[206:209], v197 offset:19456
	ds_read_b128 v[210:213], v197 offset:20480
	ds_read_b128 v[214:217], v197 offset:21504
	ds_read_b128 v[218:221], v197 offset:22528
	ds_read_b128 v[222:225], v197 offset:23552
	s_waitcnt vmcnt(8)
	s_waitcnt lgkmcnt(0)
	s_barrier
	s_waitcnt lgkmcnt(0)
	v_mfma_f32_16x16x32_bf16 v[70:73], v[62:65], v[190:193], v[70:73]
	v_mfma_f32_16x16x32_bf16 v[70:73], v[66:69], v[198:201], v[70:73]
	v_mfma_f32_16x16x32_bf16 v[58:61], v[74:77], v[190:193], v[58:61]
	v_mfma_f32_16x16x32_bf16 v[58:61], v[78:81], v[198:201], v[58:61]
	v_mfma_f32_16x16x32_bf16 v[46:49], v[62:65], v[202:205], v[46:49]
	v_mfma_f32_16x16x32_bf16 v[46:49], v[66:69], v[206:209], v[46:49]
	v_mfma_f32_16x16x32_bf16 v[42:45], v[74:77], v[202:205], v[42:45]
	v_mfma_f32_16x16x32_bf16 v[42:45], v[78:81], v[206:209], v[42:45]
	v_mfma_f32_16x16x32_bf16 v[30:33], v[62:65], v[210:213], v[30:33]
	v_mfma_f32_16x16x32_bf16 v[30:33], v[66:69], v[214:217], v[30:33]
	v_mfma_f32_16x16x32_bf16 v[26:29], v[74:77], v[210:213], v[26:29]
	v_mfma_f32_16x16x32_bf16 v[26:29], v[78:81], v[214:217], v[26:29]
	v_mfma_f32_16x16x32_bf16 v[14:17], v[62:65], v[218:221], v[14:17]
	v_mfma_f32_16x16x32_bf16 v[14:17], v[66:69], v[222:225], v[14:17]
	v_mfma_f32_16x16x32_bf16 v[10:13], v[74:77], v[218:221], v[10:13]
	v_mfma_f32_16x16x32_bf16 v[10:13], v[78:81], v[222:225], v[10:13]
	v_mfma_f32_16x16x32_bf16 v[54:57], v[146:149], v[190:193], v[54:57]
	v_mfma_f32_16x16x32_bf16 v[54:57], v[150:153], v[198:201], v[54:57]
	v_mfma_f32_16x16x32_bf16 v[50:53], v[154:157], v[190:193], v[50:53]
	v_mfma_f32_16x16x32_bf16 v[50:53], v[158:161], v[198:201], v[50:53]
	v_mfma_f32_16x16x32_bf16 v[38:41], v[146:149], v[202:205], v[38:41]
	v_mfma_f32_16x16x32_bf16 v[38:41], v[150:153], v[206:209], v[38:41]
	v_mfma_f32_16x16x32_bf16 v[34:37], v[154:157], v[202:205], v[34:37]
	v_mfma_f32_16x16x32_bf16 v[34:37], v[158:161], v[206:209], v[34:37]
	v_mfma_f32_16x16x32_bf16 v[22:25], v[146:149], v[210:213], v[22:25]
	v_mfma_f32_16x16x32_bf16 v[22:25], v[150:153], v[214:217], v[22:25]
	v_mfma_f32_16x16x32_bf16 v[18:21], v[154:157], v[210:213], v[18:21]
	v_mfma_f32_16x16x32_bf16 v[18:21], v[158:161], v[214:217], v[18:21]
	v_mfma_f32_16x16x32_bf16 v[6:9], v[146:149], v[218:221], v[6:9]
	v_mfma_f32_16x16x32_bf16 v[6:9], v[150:153], v[222:225], v[6:9]
	v_mfma_f32_16x16x32_bf16 v[2:5], v[154:157], v[218:221], v[2:5]
	v_mfma_f32_16x16x32_bf16 v[2:5], v[158:161], v[222:225], v[2:5]
	s_barrier
	s_add_i32 s55, 0, 0x18000
	s_add_i32 s56, 0, 0x1c000
	s_add_u32 s38, s38, 0x100000
	s_addc_u32 s39, s39, 0
	s_mov_b32 m0, s42
	s_nop 0
	global_load_lds_dwordx4 v168, s[38:39]
	s_mov_b32 m0, s43
	s_nop 0
	global_load_lds_dwordx4 v164, s[38:39]
	v_add_u32_e32 v78, s55, v187
	v_add_u32_e32 v158, s56, v187
	ds_read_b128 v[62:65], v78
	ds_read_b128 v[66:69], v78 offset:1024
	ds_read_b128 v[74:77], v78 offset:2048
	ds_read_b128 v[78:81], v78 offset:3072
	ds_read_b128 v[146:149], v158
	ds_read_b128 v[150:153], v158 offset:1024
	ds_read_b128 v[154:157], v158 offset:2048
	ds_read_b128 v[158:161], v158 offset:3072
	ds_read_b128 v[190:193], v197 offset:32768
	ds_read_b128 v[198:201], v197 offset:33792
	ds_read_b128 v[202:205], v197 offset:34816
	ds_read_b128 v[206:209], v197 offset:35840
	ds_read_b128 v[210:213], v197 offset:36864
	ds_read_b128 v[214:217], v197 offset:37888
	ds_read_b128 v[218:221], v197 offset:38912
	ds_read_b128 v[222:225], v197 offset:39936
	s_waitcnt vmcnt(8)
	s_waitcnt lgkmcnt(0)
	s_barrier
	s_waitcnt lgkmcnt(0)
	v_mfma_f32_16x16x32_bf16 v[142:145], v[62:65], v[190:193], v[142:145]
	v_mfma_f32_16x16x32_bf16 v[142:145], v[66:69], v[198:201], v[142:145]
	v_mfma_f32_16x16x32_bf16 v[138:141], v[74:77], v[190:193], v[138:141]
	v_mfma_f32_16x16x32_bf16 v[138:141], v[78:81], v[198:201], v[138:141]
	v_mfma_f32_16x16x32_bf16 v[126:129], v[62:65], v[202:205], v[126:129]
	v_mfma_f32_16x16x32_bf16 v[126:129], v[66:69], v[206:209], v[126:129]
	v_mfma_f32_16x16x32_bf16 v[122:125], v[74:77], v[202:205], v[122:125]
	v_mfma_f32_16x16x32_bf16 v[122:125], v[78:81], v[206:209], v[122:125]
	v_mfma_f32_16x16x32_bf16 v[110:113], v[62:65], v[210:213], v[110:113]
	v_mfma_f32_16x16x32_bf16 v[110:113], v[66:69], v[214:217], v[110:113]
	v_mfma_f32_16x16x32_bf16 v[106:109], v[74:77], v[210:213], v[106:109]
	v_mfma_f32_16x16x32_bf16 v[106:109], v[78:81], v[214:217], v[106:109]
	v_mfma_f32_16x16x32_bf16 v[94:97], v[62:65], v[218:221], v[94:97]
	v_mfma_f32_16x16x32_bf16 v[94:97], v[66:69], v[222:225], v[94:97]
	v_mfma_f32_16x16x32_bf16 v[90:93], v[74:77], v[218:221], v[90:93]
	v_mfma_f32_16x16x32_bf16 v[90:93], v[78:81], v[222:225], v[90:93]
	v_mfma_f32_16x16x32_bf16 v[134:137], v[146:149], v[190:193], v[134:137]
	v_mfma_f32_16x16x32_bf16 v[134:137], v[150:153], v[198:201], v[134:137]
	v_mfma_f32_16x16x32_bf16 v[130:133], v[154:157], v[190:193], v[130:133]
	v_mfma_f32_16x16x32_bf16 v[130:133], v[158:161], v[198:201], v[130:133]
	v_mfma_f32_16x16x32_bf16 v[118:121], v[146:149], v[202:205], v[118:121]
	v_mfma_f32_16x16x32_bf16 v[118:121], v[150:153], v[206:209], v[118:121]
	v_mfma_f32_16x16x32_bf16 v[114:117], v[154:157], v[202:205], v[114:117]
	v_mfma_f32_16x16x32_bf16 v[114:117], v[158:161], v[206:209], v[114:117]
	v_mfma_f32_16x16x32_bf16 v[102:105], v[146:149], v[210:213], v[102:105]
	v_mfma_f32_16x16x32_bf16 v[102:105], v[150:153], v[214:217], v[102:105]
	v_mfma_f32_16x16x32_bf16 v[98:101], v[154:157], v[210:213], v[98:101]
	v_mfma_f32_16x16x32_bf16 v[98:101], v[158:161], v[214:217], v[98:101]
	v_mfma_f32_16x16x32_bf16 v[86:89], v[146:149], v[218:221], v[86:89]
	v_mfma_f32_16x16x32_bf16 v[86:89], v[150:153], v[222:225], v[86:89]
	v_mfma_f32_16x16x32_bf16 v[82:85], v[154:157], v[218:221], v[82:85]
	v_mfma_f32_16x16x32_bf16 v[82:85], v[158:161], v[222:225], v[82:85]
	s_barrier
	s_add_u32 s38, s36, 0x4000
	s_addc_u32 s39, s37, 0
	s_add_i32 s55, s55, s33
	s_mov_b32 m0, s55
	s_nop 0
	global_load_lds_dwordx4 v166, s[38:39]
	s_add_i32 m0, s55, 0x2000
	s_add_u32 s36, s36, 0x104000
	s_addc_u32 s37, s37, 0
	global_load_lds_dwordx4 v162, s[38:39]
	s_add_i32 s38, s56, s33
	s_mov_b32 m0, s38
	s_nop 0
	global_load_lds_dwordx4 v166, s[36:37]
	s_add_i32 m0, s38, 0x2000
	s_nop 0
	global_load_lds_dwordx4 v162, s[36:37]
	s_mov_b32 m0, s46
	s_nop 0
	global_load_lds_dwordx4 v168, s[34:35]
	s_mov_b32 m0, s47
	s_nop 0
	global_load_lds_dwordx4 v164, s[34:35]
	ds_read_b128 v[190:193], v197 offset:49152
	ds_read_b128 v[198:201], v197 offset:50176
	ds_read_b128 v[202:205], v197 offset:51200
	ds_read_b128 v[206:209], v197 offset:52224
	ds_read_b128 v[210:213], v197 offset:53248
	ds_read_b128 v[214:217], v197 offset:54272
	ds_read_b128 v[218:221], v197 offset:55296
	ds_read_b128 v[222:225], v197 offset:56320
	s_waitcnt vmcnt(8)
	s_waitcnt lgkmcnt(0)
	s_barrier
	s_waitcnt lgkmcnt(0)
	v_mfma_f32_16x16x32_bf16 v[70:73], v[62:65], v[190:193], v[70:73]
	v_mfma_f32_16x16x32_bf16 v[70:73], v[66:69], v[198:201], v[70:73]
	v_mfma_f32_16x16x32_bf16 v[58:61], v[74:77], v[190:193], v[58:61]
	v_mfma_f32_16x16x32_bf16 v[58:61], v[78:81], v[198:201], v[58:61]
	v_mfma_f32_16x16x32_bf16 v[46:49], v[62:65], v[202:205], v[46:49]
	v_mfma_f32_16x16x32_bf16 v[46:49], v[66:69], v[206:209], v[46:49]
	v_mfma_f32_16x16x32_bf16 v[42:45], v[74:77], v[202:205], v[42:45]
	v_mfma_f32_16x16x32_bf16 v[42:45], v[78:81], v[206:209], v[42:45]
	v_mfma_f32_16x16x32_bf16 v[30:33], v[62:65], v[210:213], v[30:33]
	v_mfma_f32_16x16x32_bf16 v[30:33], v[66:69], v[214:217], v[30:33]
	v_mfma_f32_16x16x32_bf16 v[26:29], v[74:77], v[210:213], v[26:29]
	v_mfma_f32_16x16x32_bf16 v[26:29], v[78:81], v[214:217], v[26:29]
	v_mfma_f32_16x16x32_bf16 v[14:17], v[62:65], v[218:221], v[14:17]
	v_mfma_f32_16x16x32_bf16 v[14:17], v[66:69], v[222:225], v[14:17]
	v_mfma_f32_16x16x32_bf16 v[10:13], v[74:77], v[218:221], v[10:13]
	v_mfma_f32_16x16x32_bf16 v[10:13], v[78:81], v[222:225], v[10:13]
	v_mfma_f32_16x16x32_bf16 v[54:57], v[146:149], v[190:193], v[54:57]
	v_mfma_f32_16x16x32_bf16 v[54:57], v[150:153], v[198:201], v[54:57]
	v_mfma_f32_16x16x32_bf16 v[50:53], v[154:157], v[190:193], v[50:53]
	v_mfma_f32_16x16x32_bf16 v[50:53], v[158:161], v[198:201], v[50:53]
	v_mfma_f32_16x16x32_bf16 v[38:41], v[146:149], v[202:205], v[38:41]
	v_mfma_f32_16x16x32_bf16 v[38:41], v[150:153], v[206:209], v[38:41]
	v_mfma_f32_16x16x32_bf16 v[34:37], v[154:157], v[202:205], v[34:37]
	v_mfma_f32_16x16x32_bf16 v[34:37], v[158:161], v[206:209], v[34:37]
	v_mfma_f32_16x16x32_bf16 v[22:25], v[146:149], v[210:213], v[22:25]
	v_mfma_f32_16x16x32_bf16 v[22:25], v[150:153], v[214:217], v[22:25]
	v_mfma_f32_16x16x32_bf16 v[18:21], v[154:157], v[210:213], v[18:21]
	v_mfma_f32_16x16x32_bf16 v[18:21], v[158:161], v[214:217], v[18:21]
	v_mfma_f32_16x16x32_bf16 v[6:9], v[146:149], v[218:221], v[6:9]
	v_mfma_f32_16x16x32_bf16 v[6:9], v[150:153], v[222:225], v[6:9]
	v_mfma_f32_16x16x32_bf16 v[2:5], v[154:157], v[218:221], v[2:5]
	v_mfma_f32_16x16x32_bf16 v[2:5], v[158:161], v[222:225], v[2:5]
	s_barrier
	s_add_i32 s54, s54, 2
	s_add_u32 s30, s30, 0x8000
	s_addc_u32 s31, s31, 0
	s_add_u32 s52, s52, 0x8000
	s_addc_u32 s53, s53, 0
	s_cmp_gt_u32 s54, 61
	s_cbranch_scc0 .LBB0_1387
	s_and_b64 vcc, exec, s[12:13]
	s_cbranch_vccz .LBB0_1390
	s_barrier
